# ho/ao gate epilogues hand-written: all gate quads in flight, counted waits (on top of kv0 + xo residual epilogue)
# baseline (speedup 1.0000x reference)
.LBB0_227:
	v_readlane_b32 s4, v250, 25
	v_mbcnt_lo_u32_b32 v138, -1, 0
	v_mbcnt_hi_u32_b32 v138, -1, v138
	s_nop 1
	s_lshr_b32 s5, s4, 8
	s_bfe_u32 s4, s4, 0x20006
	v_and_b32_e32 v139, 15, v138
	v_lshrrev_b32_e32 v146, 4, v138
	s_lshl_b32 s5, s5, 6
	s_lshl_b32 s98, s28, 8
	s_add_u32 s5, s5, s98
	v_add_u32_e32 v139, s5, v139
	v_lshlrev_b32_e32 v147, 11, v139
	v_lshl_add_u32 v147, v146, 4, v147
	s_lshl_b32 s4, s4, 6
	v_add_u32_e32 v147, s4, v147
	v_mov_b32_e32 v148, v147
	v_readlane_b32 s98, v253, 38
	v_readlane_b32 s99, v253, 39
	s_lshl_b32 s4, s25, 9
	s_nop 1
	s_add_u32 s98, s98, s4
	s_addc_u32 s99, s99, 0
	global_load_dwordx4 v[184:187], v147, s[98:99]
	global_load_dwordx4 v[188:191], v147, s[98:99] offset:256
	v_add_u32_e32 v147, 0x8000, v147
	global_load_dwordx4 v[192:195], v147, s[98:99]
	global_load_dwordx4 v[196:199], v147, s[98:99] offset:256
	v_add_u32_e32 v147, 0x8000, v147
	global_load_dwordx4 v[200:203], v147, s[98:99]
	global_load_dwordx4 v[204:207], v147, s[98:99] offset:256
	v_add_u32_e32 v147, 0x8000, v147
	global_load_dwordx4 v[208:211], v147, s[98:99]
	global_load_dwordx4 v[212:215], v147, s[98:99] offset:256
	v_add_u32_e32 v147, 0x28000, v147
	global_load_dwordx4 v[216:219], v147, s[98:99]
	global_load_dwordx4 v[220:223], v147, s[98:99] offset:256
	v_add_u32_e32 v147, 0x8000, v147
	global_load_dwordx4 v[224:227], v147, s[98:99]
	global_load_dwordx4 v[228:231], v147, s[98:99] offset:256
	v_add_u32_e32 v147, 0x8000, v147
	global_load_dwordx4 v[232:235], v147, s[98:99]
	global_load_dwordx4 v[236:239], v147, s[98:99] offset:256
	v_add_u32_e32 v147, 0x8000, v147
	global_load_dwordx4 v[240:243], v147, s[98:99]
	global_load_dwordx4 v[244:247], v147, s[98:99] offset:256
	s_waitcnt vmcnt(15)
	v_lshlrev_b32_e32 v182, 16, v184
	v_and_b32_e32 v183, 0xffff0000, v184
	v_pk_mul_f32 v[126:127], v[126:127], v[182:183]
	v_lshlrev_b32_e32 v248, 16, v185
	v_and_b32_e32 v249, 0xffff0000, v185
	v_pk_mul_f32 v[128:129], v[128:129], v[248:249]
	v_lshlrev_b32_e32 v182, 16, v186
	v_and_b32_e32 v183, 0xffff0000, v186
	v_pk_mul_f32 v[122:123], v[122:123], v[182:183]
	v_lshlrev_b32_e32 v248, 16, v187
	v_and_b32_e32 v249, 0xffff0000, v187
	v_pk_mul_f32 v[124:125], v[124:125], v[248:249]
	v_cvt_pk_bf16_f32 v126, v126, v127
	v_cvt_pk_bf16_f32 v127, v128, v129
	v_cvt_pk_bf16_f32 v128, v122, v123
	v_cvt_pk_bf16_f32 v129, v124, v125
	global_store_dwordx4 v148, v[126:129], s[98:99]
	s_waitcnt vmcnt(15)
	v_lshlrev_b32_e32 v182, 16, v188
	v_and_b32_e32 v183, 0xffff0000, v188
	v_pk_mul_f32 v[118:119], v[118:119], v[182:183]
	v_lshlrev_b32_e32 v248, 16, v189
	v_and_b32_e32 v249, 0xffff0000, v189
	v_pk_mul_f32 v[120:121], v[120:121], v[248:249]
	v_lshlrev_b32_e32 v182, 16, v190
	v_and_b32_e32 v183, 0xffff0000, v190
	v_pk_mul_f32 v[110:111], v[110:111], v[182:183]
	v_lshlrev_b32_e32 v248, 16, v191
	v_and_b32_e32 v249, 0xffff0000, v191
	v_pk_mul_f32 v[112:113], v[112:113], v[248:249]
	v_cvt_pk_bf16_f32 v118, v118, v119
	v_cvt_pk_bf16_f32 v119, v120, v121
	v_cvt_pk_bf16_f32 v120, v110, v111
	v_cvt_pk_bf16_f32 v121, v112, v113
	global_store_dwordx4 v148, v[118:121], s[98:99] offset:256
	v_add_u32_e32 v148, 0x8000, v148
	s_waitcnt vmcnt(15)
	v_lshlrev_b32_e32 v182, 16, v192
	v_and_b32_e32 v183, 0xffff0000, v192
	v_pk_mul_f32 v[114:115], v[114:115], v[182:183]
	v_lshlrev_b32_e32 v248, 16, v193
	v_and_b32_e32 v249, 0xffff0000, v193
	v_pk_mul_f32 v[116:117], v[116:117], v[248:249]
	v_lshlrev_b32_e32 v182, 16, v194
	v_and_b32_e32 v183, 0xffff0000, v194
	v_pk_mul_f32 v[106:107], v[106:107], v[182:183]
	v_lshlrev_b32_e32 v248, 16, v195
	v_and_b32_e32 v249, 0xffff0000, v195
	v_pk_mul_f32 v[108:109], v[108:109], v[248:249]
	v_cvt_pk_bf16_f32 v114, v114, v115
	v_cvt_pk_bf16_f32 v115, v116, v117
	v_cvt_pk_bf16_f32 v116, v106, v107
	v_cvt_pk_bf16_f32 v117, v108, v109
	global_store_dwordx4 v148, v[114:117], s[98:99]
	s_waitcnt vmcnt(15)
	v_lshlrev_b32_e32 v182, 16, v196
	v_and_b32_e32 v183, 0xffff0000, v196
	v_pk_mul_f32 v[102:103], v[102:103], v[182:183]
	v_lshlrev_b32_e32 v248, 16, v197
	v_and_b32_e32 v249, 0xffff0000, v197
	v_pk_mul_f32 v[104:105], v[104:105], v[248:249]
	v_lshlrev_b32_e32 v182, 16, v198
	v_and_b32_e32 v183, 0xffff0000, v198
	v_pk_mul_f32 v[94:95], v[94:95], v[182:183]
	v_lshlrev_b32_e32 v248, 16, v199
	v_and_b32_e32 v249, 0xffff0000, v199
	v_pk_mul_f32 v[96:97], v[96:97], v[248:249]
	v_cvt_pk_bf16_f32 v102, v102, v103
	v_cvt_pk_bf16_f32 v103, v104, v105
	v_cvt_pk_bf16_f32 v104, v94, v95
	v_cvt_pk_bf16_f32 v105, v96, v97
	global_store_dwordx4 v148, v[102:105], s[98:99] offset:256
	v_add_u32_e32 v148, 0x8000, v148
	s_waitcnt vmcnt(15)
	v_lshlrev_b32_e32 v182, 16, v200
	v_and_b32_e32 v183, 0xffff0000, v200
	v_pk_mul_f32 v[98:99], v[98:99], v[182:183]
	v_lshlrev_b32_e32 v248, 16, v201
	v_and_b32_e32 v249, 0xffff0000, v201
	v_pk_mul_f32 v[100:101], v[100:101], v[248:249]
	v_lshlrev_b32_e32 v182, 16, v202
	v_and_b32_e32 v183, 0xffff0000, v202
	v_pk_mul_f32 v[90:91], v[90:91], v[182:183]
	v_lshlrev_b32_e32 v248, 16, v203
	v_and_b32_e32 v249, 0xffff0000, v203
	v_pk_mul_f32 v[92:93], v[92:93], v[248:249]
	v_cvt_pk_bf16_f32 v98, v98, v99
	v_cvt_pk_bf16_f32 v99, v100, v101
	v_cvt_pk_bf16_f32 v100, v90, v91
	v_cvt_pk_bf16_f32 v101, v92, v93
	global_store_dwordx4 v148, v[98:101], s[98:99]
	s_waitcnt vmcnt(15)
	v_lshlrev_b32_e32 v182, 16, v204
	v_and_b32_e32 v183, 0xffff0000, v204
	v_pk_mul_f32 v[86:87], v[86:87], v[182:183]
	v_lshlrev_b32_e32 v248, 16, v205
	v_and_b32_e32 v249, 0xffff0000, v205
	v_pk_mul_f32 v[88:89], v[88:89], v[248:249]
	v_lshlrev_b32_e32 v182, 16, v206
	v_and_b32_e32 v183, 0xffff0000, v206
	v_pk_mul_f32 v[78:79], v[78:79], v[182:183]
	v_lshlrev_b32_e32 v248, 16, v207
	v_and_b32_e32 v249, 0xffff0000, v207
	v_pk_mul_f32 v[80:81], v[80:81], v[248:249]
	v_cvt_pk_bf16_f32 v86, v86, v87
	v_cvt_pk_bf16_f32 v87, v88, v89
	v_cvt_pk_bf16_f32 v88, v78, v79
	v_cvt_pk_bf16_f32 v89, v80, v81
	global_store_dwordx4 v148, v[86:89], s[98:99] offset:256
	v_add_u32_e32 v148, 0x8000, v148
	s_waitcnt vmcnt(15)
	v_lshlrev_b32_e32 v182, 16, v208
	v_and_b32_e32 v183, 0xffff0000, v208
	v_pk_mul_f32 v[82:83], v[82:83], v[182:183]
	v_lshlrev_b32_e32 v248, 16, v209
	v_and_b32_e32 v249, 0xffff0000, v209
	v_pk_mul_f32 v[84:85], v[84:85], v[248:249]
	v_lshlrev_b32_e32 v182, 16, v210
	v_and_b32_e32 v183, 0xffff0000, v210
	v_pk_mul_f32 v[74:75], v[74:75], v[182:183]
	v_lshlrev_b32_e32 v248, 16, v211
	v_and_b32_e32 v249, 0xffff0000, v211
	v_pk_mul_f32 v[76:77], v[76:77], v[248:249]
	v_cvt_pk_bf16_f32 v82, v82, v83
	v_cvt_pk_bf16_f32 v83, v84, v85
	v_cvt_pk_bf16_f32 v84, v74, v75
	v_cvt_pk_bf16_f32 v85, v76, v77
	global_store_dwordx4 v148, v[82:85], s[98:99]
	s_waitcnt vmcnt(15)
	v_lshlrev_b32_e32 v182, 16, v212
	v_and_b32_e32 v183, 0xffff0000, v212
	v_pk_mul_f32 v[70:71], v[70:71], v[182:183]
	v_lshlrev_b32_e32 v248, 16, v213
	v_and_b32_e32 v249, 0xffff0000, v213
	v_pk_mul_f32 v[72:73], v[72:73], v[248:249]
	v_lshlrev_b32_e32 v182, 16, v214
	v_and_b32_e32 v183, 0xffff0000, v214
	v_pk_mul_f32 v[66:67], v[66:67], v[182:183]
	v_lshlrev_b32_e32 v248, 16, v215
	v_and_b32_e32 v249, 0xffff0000, v215
	v_pk_mul_f32 v[68:69], v[68:69], v[248:249]
	v_cvt_pk_bf16_f32 v70, v70, v71
	v_cvt_pk_bf16_f32 v71, v72, v73
	v_cvt_pk_bf16_f32 v72, v66, v67
	v_cvt_pk_bf16_f32 v73, v68, v69
	global_store_dwordx4 v148, v[70:73], s[98:99] offset:256
	v_add_u32_e32 v148, 0x28000, v148
	s_waitcnt vmcnt(15)
	v_lshlrev_b32_e32 v182, 16, v216
	v_and_b32_e32 v183, 0xffff0000, v216
	v_pk_mul_f32 v[60:61], v[60:61], v[182:183]
	v_lshlrev_b32_e32 v248, 16, v217
	v_and_b32_e32 v249, 0xffff0000, v217
	v_pk_mul_f32 v[62:63], v[62:63], v[248:249]
	v_lshlrev_b32_e32 v182, 16, v218
	v_and_b32_e32 v183, 0xffff0000, v218
	v_pk_mul_f32 v[56:57], v[56:57], v[182:183]
	v_lshlrev_b32_e32 v248, 16, v219
	v_and_b32_e32 v249, 0xffff0000, v219
	v_pk_mul_f32 v[58:59], v[58:59], v[248:249]
	v_cvt_pk_bf16_f32 v60, v60, v61
	v_cvt_pk_bf16_f32 v61, v62, v63
	v_cvt_pk_bf16_f32 v62, v56, v57
	v_cvt_pk_bf16_f32 v63, v58, v59
	global_store_dwordx4 v148, v[60:63], s[98:99]
	s_waitcnt vmcnt(15)
	v_lshlrev_b32_e32 v182, 16, v220
	v_and_b32_e32 v183, 0xffff0000, v220
	v_pk_mul_f32 v[52:53], v[52:53], v[182:183]
	v_lshlrev_b32_e32 v248, 16, v221
	v_and_b32_e32 v249, 0xffff0000, v221
	v_pk_mul_f32 v[54:55], v[54:55], v[248:249]
	v_lshlrev_b32_e32 v182, 16, v222
	v_and_b32_e32 v183, 0xffff0000, v222
	v_pk_mul_f32 v[44:45], v[44:45], v[182:183]
	v_lshlrev_b32_e32 v248, 16, v223
	v_and_b32_e32 v249, 0xffff0000, v223
	v_pk_mul_f32 v[46:47], v[46:47], v[248:249]
	v_cvt_pk_bf16_f32 v52, v52, v53
	v_cvt_pk_bf16_f32 v53, v54, v55
	v_cvt_pk_bf16_f32 v54, v44, v45
	v_cvt_pk_bf16_f32 v55, v46, v47
	global_store_dwordx4 v148, v[52:55], s[98:99] offset:256
	v_add_u32_e32 v148, 0x8000, v148
	s_waitcnt vmcnt(15)
	v_lshlrev_b32_e32 v182, 16, v224
	v_and_b32_e32 v183, 0xffff0000, v224
	v_pk_mul_f32 v[48:49], v[48:49], v[182:183]
	v_lshlrev_b32_e32 v248, 16, v225
	v_and_b32_e32 v249, 0xffff0000, v225
	v_pk_mul_f32 v[50:51], v[50:51], v[248:249]
	v_lshlrev_b32_e32 v182, 16, v226
	v_and_b32_e32 v183, 0xffff0000, v226
	v_pk_mul_f32 v[40:41], v[40:41], v[182:183]
	v_lshlrev_b32_e32 v248, 16, v227
	v_and_b32_e32 v249, 0xffff0000, v227
	v_pk_mul_f32 v[42:43], v[42:43], v[248:249]
	v_cvt_pk_bf16_f32 v48, v48, v49
	v_cvt_pk_bf16_f32 v49, v50, v51
	v_cvt_pk_bf16_f32 v50, v40, v41
	v_cvt_pk_bf16_f32 v51, v42, v43
	global_store_dwordx4 v148, v[48:51], s[98:99]
	s_waitcnt vmcnt(15)
	v_lshlrev_b32_e32 v182, 16, v228
	v_and_b32_e32 v183, 0xffff0000, v228
	v_pk_mul_f32 v[36:37], v[36:37], v[182:183]
	v_lshlrev_b32_e32 v248, 16, v229
	v_and_b32_e32 v249, 0xffff0000, v229
	v_pk_mul_f32 v[38:39], v[38:39], v[248:249]
	v_lshlrev_b32_e32 v182, 16, v230
	v_and_b32_e32 v183, 0xffff0000, v230
	v_pk_mul_f32 v[28:29], v[28:29], v[182:183]
	v_lshlrev_b32_e32 v248, 16, v231
	v_and_b32_e32 v249, 0xffff0000, v231
	v_pk_mul_f32 v[30:31], v[30:31], v[248:249]
	v_cvt_pk_bf16_f32 v36, v36, v37
	v_cvt_pk_bf16_f32 v37, v38, v39
	v_cvt_pk_bf16_f32 v38, v28, v29
	v_cvt_pk_bf16_f32 v39, v30, v31
	global_store_dwordx4 v148, v[36:39], s[98:99] offset:256
	v_add_u32_e32 v148, 0x8000, v148
	s_waitcnt vmcnt(15)
	v_lshlrev_b32_e32 v182, 16, v232
	v_and_b32_e32 v183, 0xffff0000, v232
	v_pk_mul_f32 v[32:33], v[32:33], v[182:183]
	v_lshlrev_b32_e32 v248, 16, v233
	v_and_b32_e32 v249, 0xffff0000, v233
	v_pk_mul_f32 v[34:35], v[34:35], v[248:249]
	v_lshlrev_b32_e32 v182, 16, v234
	v_and_b32_e32 v183, 0xffff0000, v234
	v_pk_mul_f32 v[24:25], v[24:25], v[182:183]
	v_lshlrev_b32_e32 v248, 16, v235
	v_and_b32_e32 v249, 0xffff0000, v235
	v_pk_mul_f32 v[26:27], v[26:27], v[248:249]
	v_cvt_pk_bf16_f32 v32, v32, v33
	v_cvt_pk_bf16_f32 v33, v34, v35
	v_cvt_pk_bf16_f32 v34, v24, v25
	v_cvt_pk_bf16_f32 v35, v26, v27
	global_store_dwordx4 v148, v[32:35], s[98:99]
	s_waitcnt vmcnt(15)
	v_lshlrev_b32_e32 v182, 16, v236
	v_and_b32_e32 v183, 0xffff0000, v236
	v_pk_mul_f32 v[20:21], v[20:21], v[182:183]
	v_lshlrev_b32_e32 v248, 16, v237
	v_and_b32_e32 v249, 0xffff0000, v237
	v_pk_mul_f32 v[22:23], v[22:23], v[248:249]
	v_lshlrev_b32_e32 v182, 16, v238
	v_and_b32_e32 v183, 0xffff0000, v238
	v_pk_mul_f32 v[12:13], v[12:13], v[182:183]
	v_lshlrev_b32_e32 v248, 16, v239
	v_and_b32_e32 v249, 0xffff0000, v239
	v_pk_mul_f32 v[14:15], v[14:15], v[248:249]
	v_cvt_pk_bf16_f32 v20, v20, v21
	v_cvt_pk_bf16_f32 v21, v22, v23
	v_cvt_pk_bf16_f32 v22, v12, v13
	v_cvt_pk_bf16_f32 v23, v14, v15
	global_store_dwordx4 v148, v[20:23], s[98:99] offset:256
	v_add_u32_e32 v148, 0x8000, v148
	s_waitcnt vmcnt(15)
	v_lshlrev_b32_e32 v182, 16, v240
	v_and_b32_e32 v183, 0xffff0000, v240
	v_pk_mul_f32 v[16:17], v[16:17], v[182:183]
	v_lshlrev_b32_e32 v248, 16, v241
	v_and_b32_e32 v249, 0xffff0000, v241
	v_pk_mul_f32 v[18:19], v[18:19], v[248:249]
	v_lshlrev_b32_e32 v182, 16, v242
	v_and_b32_e32 v183, 0xffff0000, v242
	v_pk_mul_f32 v[8:9], v[8:9], v[182:183]
	v_lshlrev_b32_e32 v248, 16, v243
	v_and_b32_e32 v249, 0xffff0000, v243
	v_pk_mul_f32 v[10:11], v[10:11], v[248:249]
	v_cvt_pk_bf16_f32 v16, v16, v17
	v_cvt_pk_bf16_f32 v17, v18, v19
	v_cvt_pk_bf16_f32 v18, v8, v9
	v_cvt_pk_bf16_f32 v19, v10, v11
	global_store_dwordx4 v148, v[16:19], s[98:99]
	s_waitcnt vmcnt(15)
	v_lshlrev_b32_e32 v182, 16, v244
	v_and_b32_e32 v183, 0xffff0000, v244
	v_pk_mul_f32 v[4:5], v[4:5], v[182:183]
	v_lshlrev_b32_e32 v248, 16, v245
	v_and_b32_e32 v249, 0xffff0000, v245
	v_pk_mul_f32 v[6:7], v[6:7], v[248:249]
	v_lshlrev_b32_e32 v182, 16, v246
	v_and_b32_e32 v183, 0xffff0000, v246
	v_pk_mul_f32 v[0:1], v[0:1], v[182:183]
	v_lshlrev_b32_e32 v248, 16, v247
	v_and_b32_e32 v249, 0xffff0000, v247
	v_pk_mul_f32 v[2:3], v[2:3], v[248:249]
	v_cvt_pk_bf16_f32 v4, v4, v5
	v_cvt_pk_bf16_f32 v5, v6, v7
	v_cvt_pk_bf16_f32 v6, v0, v1
	v_cvt_pk_bf16_f32 v7, v2, v3
	global_store_dwordx4 v148, v[4:7], s[98:99] offset:256
	s_mov_b64 s[4:5], -1
	s_andn2_b64 vcc, exec, s[40:41]
	s_branch .Lho_done
	v_lshl_add_u32 v146, s28, 8, v170
	v_lshl_or_b32 v148, s25, 8, v172
	v_ashrrev_i32_e32 v147, 31, v146
	v_readlane_b32 s4, v253, 38
	v_lshlrev_b64 v[174:175], 11, v[146:147]
	v_readlane_b32 s5, v253, 39
	v_ashrrev_i32_e32 v149, 31, v148
	v_lshlrev_b64 v[148:149], 1, v[148:149]
	v_lshl_add_u64 v[174:175], s[4:5], 0, v[174:175]
	v_lshl_add_u64 v[174:175], v[174:175], 0, v[148:149]
	global_load_dwordx4 v[184:187], v[174:175], off
	s_andn2_b64 vcc, exec, s[40:41]
	s_waitcnt vmcnt(0)
	v_lshlrev_b32_e32 v138, 16, v184
	v_and_b32_e32 v139, 0xffff0000, v184
	v_lshlrev_b32_e32 v147, 16, v185
	v_and_b32_e32 v182, 0xffff0000, v185
	v_lshlrev_b32_e32 v183, 16, v186
	v_and_b32_e32 v184, 0xffff0000, v186
	v_and_b32_e32 v186, 0xffff0000, v187
	v_lshlrev_b32_e32 v185, 16, v187
	v_mul_f32_e32 v126, v126, v138
	v_mul_f32_e32 v127, v127, v139
	v_mul_f32_e32 v128, v128, v147
	v_mul_f32_e32 v129, v129, v182
	v_mul_f32_e32 v125, v125, v186
	v_mul_f32_e32 v138, v122, v183
	v_mul_f32_e32 v139, v123, v184
	v_mul_f32_e32 v147, v124, v185
	v_cvt_pk_bf16_f32 v122, v126, v127
	v_cvt_pk_bf16_f32 v123, v128, v129
	v_cvt_pk_bf16_f32 v124, v138, v139
	v_cvt_pk_bf16_f32 v125, v147, v125
	global_load_dwordx4 v[126:129], v[174:175], off offset:256
	v_or_b32_e32 v182, 16, v146
	v_ashrrev_i32_e32 v183, 31, v182
	v_lshlrev_b64 v[182:183], 11, v[182:183]
	v_lshl_add_u64 v[182:183], s[4:5], 0, v[182:183]
	global_store_dwordx4 v[174:175], v[122:125], off
	v_lshl_add_u64 v[182:183], v[182:183], 0, v[148:149]
	s_waitcnt vmcnt(1)
	v_lshlrev_b32_e32 v122, 16, v126
	v_and_b32_e32 v123, 0xffff0000, v126
	v_lshlrev_b32_e32 v124, 16, v127
	v_and_b32_e32 v125, 0xffff0000, v127
	v_lshlrev_b32_e32 v126, 16, v128
	v_and_b32_e32 v127, 0xffff0000, v128
	v_lshlrev_b32_e32 v128, 16, v129
	v_and_b32_e32 v129, 0xffff0000, v129
	v_mul_f32_e32 v118, v118, v122
	v_mul_f32_e32 v119, v119, v123
	v_mul_f32_e32 v120, v120, v124
	v_mul_f32_e32 v121, v121, v125
	v_mul_f32_e32 v113, v113, v129
	v_mul_f32_e32 v122, v110, v126
	v_mul_f32_e32 v123, v111, v127
	v_mul_f32_e32 v124, v112, v128
	v_cvt_pk_bf16_f32 v110, v118, v119
	v_cvt_pk_bf16_f32 v111, v120, v121
	v_cvt_pk_bf16_f32 v112, v122, v123
	v_cvt_pk_bf16_f32 v113, v124, v113
	global_load_dwordx4 v[118:121], v[182:183], off
	s_nop 0
	global_store_dwordx4 v[174:175], v[110:113], off offset:256
	s_waitcnt vmcnt(1)
	s_nop 0
	v_lshlrev_b32_e32 v110, 16, v118
	v_and_b32_e32 v111, 0xffff0000, v118
	v_lshlrev_b32_e32 v112, 16, v119
	v_and_b32_e32 v113, 0xffff0000, v119
	v_lshlrev_b32_e32 v118, 16, v120
	v_and_b32_e32 v119, 0xffff0000, v120
	v_lshlrev_b32_e32 v120, 16, v121
	v_and_b32_e32 v121, 0xffff0000, v121
	v_mul_f32_e32 v110, v114, v110
	v_mul_f32_e32 v111, v115, v111
	v_mul_f32_e32 v112, v116, v112
	v_mul_f32_e32 v113, v117, v113
	v_mul_f32_e32 v109, v109, v121
	v_mul_f32_e32 v114, v106, v118
	v_mul_f32_e32 v115, v107, v119
	v_mul_f32_e32 v116, v108, v120
	v_cvt_pk_bf16_f32 v106, v110, v111
	v_cvt_pk_bf16_f32 v107, v112, v113
	v_cvt_pk_bf16_f32 v108, v114, v115
	v_cvt_pk_bf16_f32 v109, v116, v109
	global_load_dwordx4 v[110:113], v[182:183], off offset:256
	v_or_b32_e32 v114, 32, v146
	v_ashrrev_i32_e32 v115, 31, v114
	v_lshlrev_b64 v[114:115], 11, v[114:115]
	v_lshl_add_u64 v[114:115], s[4:5], 0, v[114:115]
	global_store_dwordx4 v[182:183], v[106:109], off
	v_lshl_add_u64 v[114:115], v[114:115], 0, v[148:149]
	s_waitcnt vmcnt(1)
	v_lshlrev_b32_e32 v106, 16, v110
	v_and_b32_e32 v107, 0xffff0000, v110
	v_lshlrev_b32_e32 v108, 16, v111
	v_and_b32_e32 v109, 0xffff0000, v111
	v_lshlrev_b32_e32 v110, 16, v112
	v_and_b32_e32 v111, 0xffff0000, v112
	v_lshlrev_b32_e32 v112, 16, v113
	v_and_b32_e32 v113, 0xffff0000, v113
	v_mul_f32_e32 v102, v102, v106
	v_mul_f32_e32 v103, v103, v107
	v_mul_f32_e32 v104, v104, v108
	v_mul_f32_e32 v105, v105, v109
	v_mul_f32_e32 v97, v97, v113
	v_mul_f32_e32 v106, v94, v110
	v_mul_f32_e32 v107, v95, v111
	v_mul_f32_e32 v108, v96, v112
	v_cvt_pk_bf16_f32 v94, v102, v103
	v_cvt_pk_bf16_f32 v95, v104, v105
	v_cvt_pk_bf16_f32 v96, v106, v107
	v_cvt_pk_bf16_f32 v97, v108, v97
	global_load_dwordx4 v[102:105], v[114:115], off
	s_nop 0
	global_store_dwordx4 v[182:183], v[94:97], off offset:256
	s_waitcnt vmcnt(1)
	s_nop 0
	v_lshlrev_b32_e32 v94, 16, v102
	v_and_b32_e32 v95, 0xffff0000, v102
	v_lshlrev_b32_e32 v96, 16, v103
	v_and_b32_e32 v97, 0xffff0000, v103
	v_lshlrev_b32_e32 v102, 16, v104
	v_and_b32_e32 v103, 0xffff0000, v104
	v_lshlrev_b32_e32 v104, 16, v105
	v_and_b32_e32 v105, 0xffff0000, v105
	v_mul_f32_e32 v94, v98, v94
	v_mul_f32_e32 v95, v99, v95
	v_mul_f32_e32 v96, v100, v96
	v_mul_f32_e32 v97, v101, v97
	v_mul_f32_e32 v93, v93, v105
	v_mul_f32_e32 v98, v90, v102
	v_mul_f32_e32 v99, v91, v103
	v_mul_f32_e32 v100, v92, v104
	v_cvt_pk_bf16_f32 v90, v94, v95
	v_cvt_pk_bf16_f32 v91, v96, v97
	v_cvt_pk_bf16_f32 v92, v98, v99
	v_cvt_pk_bf16_f32 v93, v100, v93
	global_load_dwordx4 v[94:97], v[114:115], off offset:256
	v_or_b32_e32 v98, 48, v146
	v_ashrrev_i32_e32 v99, 31, v98
	v_lshlrev_b64 v[98:99], 11, v[98:99]
	v_lshl_add_u64 v[98:99], s[4:5], 0, v[98:99]
	global_store_dwordx4 v[114:115], v[90:93], off
	v_lshl_add_u64 v[98:99], v[98:99], 0, v[148:149]
	s_waitcnt vmcnt(1)
	v_lshlrev_b32_e32 v90, 16, v94
	v_and_b32_e32 v91, 0xffff0000, v94
	v_lshlrev_b32_e32 v92, 16, v95
	v_and_b32_e32 v93, 0xffff0000, v95
	v_lshlrev_b32_e32 v94, 16, v96
	v_and_b32_e32 v95, 0xffff0000, v96
	v_lshlrev_b32_e32 v96, 16, v97
	v_and_b32_e32 v97, 0xffff0000, v97
	v_mul_f32_e32 v86, v86, v90
	v_mul_f32_e32 v87, v87, v91
	v_mul_f32_e32 v88, v88, v92
	v_mul_f32_e32 v89, v89, v93
	v_mul_f32_e32 v81, v81, v97
	v_mul_f32_e32 v90, v78, v94
	v_mul_f32_e32 v91, v79, v95
	v_mul_f32_e32 v92, v80, v96
	v_cvt_pk_bf16_f32 v78, v86, v87
	v_cvt_pk_bf16_f32 v79, v88, v89
	v_cvt_pk_bf16_f32 v80, v90, v91
	v_cvt_pk_bf16_f32 v81, v92, v81
	global_load_dwordx4 v[86:89], v[98:99], off
	s_nop 0
	global_store_dwordx4 v[114:115], v[78:81], off offset:256
	s_waitcnt vmcnt(1)
	s_nop 0
	v_lshlrev_b32_e32 v78, 16, v86
	v_and_b32_e32 v79, 0xffff0000, v86
	v_lshlrev_b32_e32 v80, 16, v87
	v_and_b32_e32 v81, 0xffff0000, v87
	v_lshlrev_b32_e32 v86, 16, v88
	v_and_b32_e32 v87, 0xffff0000, v88
	v_lshlrev_b32_e32 v88, 16, v89
	v_and_b32_e32 v89, 0xffff0000, v89
	v_mul_f32_e32 v78, v82, v78
	v_mul_f32_e32 v79, v83, v79
	v_mul_f32_e32 v80, v84, v80
	v_mul_f32_e32 v81, v85, v81
	v_mul_f32_e32 v77, v77, v89
	v_mul_f32_e32 v82, v74, v86
	v_mul_f32_e32 v83, v75, v87
	v_mul_f32_e32 v84, v76, v88
	v_cvt_pk_bf16_f32 v74, v78, v79
	v_cvt_pk_bf16_f32 v75, v80, v81
	v_cvt_pk_bf16_f32 v76, v82, v83
	v_cvt_pk_bf16_f32 v77, v84, v77
	global_load_dwordx4 v[78:81], v[98:99], off offset:256
	v_add_u32_e32 v82, 0x80, v146
	v_ashrrev_i32_e32 v83, 31, v82
	v_lshlrev_b64 v[82:83], 11, v[82:83]
	v_lshl_add_u64 v[82:83], s[4:5], 0, v[82:83]
	global_store_dwordx4 v[98:99], v[74:77], off
	v_lshl_add_u64 v[82:83], v[82:83], 0, v[148:149]
	s_waitcnt vmcnt(1)
	v_lshlrev_b32_e32 v74, 16, v78
	v_and_b32_e32 v75, 0xffff0000, v78
	v_lshlrev_b32_e32 v76, 16, v79
	v_and_b32_e32 v77, 0xffff0000, v79
	v_lshlrev_b32_e32 v78, 16, v80
	v_and_b32_e32 v79, 0xffff0000, v80
	v_lshlrev_b32_e32 v80, 16, v81
	v_and_b32_e32 v81, 0xffff0000, v81
	v_mul_f32_e32 v70, v70, v74
	v_mul_f32_e32 v71, v71, v75
	v_mul_f32_e32 v72, v72, v76
	v_mul_f32_e32 v73, v73, v77
	v_mul_f32_e32 v69, v69, v81
	v_mul_f32_e32 v74, v66, v78
	v_mul_f32_e32 v75, v67, v79
	v_mul_f32_e32 v76, v68, v80
	v_cvt_pk_bf16_f32 v66, v70, v71
	v_cvt_pk_bf16_f32 v67, v72, v73
	v_cvt_pk_bf16_f32 v68, v74, v75
	v_cvt_pk_bf16_f32 v69, v76, v69
	global_load_dwordx4 v[70:73], v[82:83], off
	s_nop 0
	global_store_dwordx4 v[98:99], v[66:69], off offset:256
	s_waitcnt vmcnt(1)
	s_nop 0
	v_lshlrev_b32_e32 v66, 16, v70
	v_and_b32_e32 v67, 0xffff0000, v70
	v_lshlrev_b32_e32 v68, 16, v71
	v_and_b32_e32 v69, 0xffff0000, v71
	v_lshlrev_b32_e32 v70, 16, v72
	v_and_b32_e32 v71, 0xffff0000, v72
	v_lshlrev_b32_e32 v72, 16, v73
	v_and_b32_e32 v73, 0xffff0000, v73
	v_mul_f32_e32 v60, v60, v66
	v_mul_f32_e32 v61, v61, v67
	v_mul_f32_e32 v62, v62, v68
	v_mul_f32_e32 v63, v63, v69
	v_mul_f32_e32 v59, v59, v73
	v_mul_f32_e32 v66, v56, v70
	v_mul_f32_e32 v67, v57, v71
	v_mul_f32_e32 v68, v58, v72
	v_cvt_pk_bf16_f32 v56, v60, v61
	v_cvt_pk_bf16_f32 v57, v62, v63
	v_cvt_pk_bf16_f32 v58, v66, v67
	v_cvt_pk_bf16_f32 v59, v68, v59
	global_load_dwordx4 v[60:63], v[82:83], off offset:256
	v_add_u32_e32 v66, 0x90, v146
	v_ashrrev_i32_e32 v67, 31, v66
	v_lshlrev_b64 v[66:67], 11, v[66:67]
	v_lshl_add_u64 v[66:67], s[4:5], 0, v[66:67]
	global_store_dwordx4 v[82:83], v[56:59], off
	v_lshl_add_u64 v[66:67], v[66:67], 0, v[148:149]
	s_waitcnt vmcnt(1)
	v_lshlrev_b32_e32 v56, 16, v60
	v_and_b32_e32 v57, 0xffff0000, v60
	v_lshlrev_b32_e32 v58, 16, v61
	v_and_b32_e32 v59, 0xffff0000, v61
	v_lshlrev_b32_e32 v60, 16, v62
	v_and_b32_e32 v61, 0xffff0000, v62
	v_lshlrev_b32_e32 v62, 16, v63
	v_and_b32_e32 v63, 0xffff0000, v63
	v_mul_f32_e32 v52, v52, v56
	v_mul_f32_e32 v53, v53, v57
	v_mul_f32_e32 v54, v54, v58
	v_mul_f32_e32 v55, v55, v59
	v_mul_f32_e32 v47, v47, v63
	v_mul_f32_e32 v56, v44, v60
	v_mul_f32_e32 v57, v45, v61
	v_mul_f32_e32 v58, v46, v62
	v_cvt_pk_bf16_f32 v44, v52, v53
	v_cvt_pk_bf16_f32 v45, v54, v55
	v_cvt_pk_bf16_f32 v46, v56, v57
	v_cvt_pk_bf16_f32 v47, v58, v47
	global_load_dwordx4 v[52:55], v[66:67], off
	s_nop 0
	global_store_dwordx4 v[82:83], v[44:47], off offset:256
	s_waitcnt vmcnt(1)
	s_nop 0
	v_lshlrev_b32_e32 v44, 16, v52
	v_and_b32_e32 v45, 0xffff0000, v52
	v_lshlrev_b32_e32 v46, 16, v53
	v_and_b32_e32 v47, 0xffff0000, v53
	v_lshlrev_b32_e32 v52, 16, v54
	v_and_b32_e32 v53, 0xffff0000, v54
	v_lshlrev_b32_e32 v54, 16, v55
	v_and_b32_e32 v55, 0xffff0000, v55
	v_mul_f32_e32 v44, v48, v44
	v_mul_f32_e32 v45, v49, v45
	v_mul_f32_e32 v46, v50, v46
	v_mul_f32_e32 v47, v51, v47
	v_mul_f32_e32 v43, v43, v55
	v_mul_f32_e32 v48, v40, v52
	v_mul_f32_e32 v49, v41, v53
	v_mul_f32_e32 v50, v42, v54
	v_cvt_pk_bf16_f32 v40, v44, v45
	v_cvt_pk_bf16_f32 v41, v46, v47
	v_cvt_pk_bf16_f32 v42, v48, v49
	v_cvt_pk_bf16_f32 v43, v50, v43
	global_load_dwordx4 v[44:47], v[66:67], off offset:256
	v_add_u32_e32 v48, 0xa0, v146
	v_ashrrev_i32_e32 v49, 31, v48
	v_lshlrev_b64 v[48:49], 11, v[48:49]
	v_lshl_add_u64 v[48:49], s[4:5], 0, v[48:49]
	global_store_dwordx4 v[66:67], v[40:43], off
	v_lshl_add_u64 v[48:49], v[48:49], 0, v[148:149]
	s_waitcnt vmcnt(1)
	v_lshlrev_b32_e32 v40, 16, v44
	v_and_b32_e32 v41, 0xffff0000, v44
	v_lshlrev_b32_e32 v42, 16, v45
	v_and_b32_e32 v43, 0xffff0000, v45
	v_lshlrev_b32_e32 v44, 16, v46
	v_and_b32_e32 v45, 0xffff0000, v46
	v_lshlrev_b32_e32 v46, 16, v47
	v_and_b32_e32 v47, 0xffff0000, v47
	v_mul_f32_e32 v36, v36, v40
	v_mul_f32_e32 v37, v37, v41
	v_mul_f32_e32 v38, v38, v42
	v_mul_f32_e32 v39, v39, v43
	v_mul_f32_e32 v31, v31, v47
	v_mul_f32_e32 v40, v28, v44
	v_mul_f32_e32 v41, v29, v45
	v_mul_f32_e32 v42, v30, v46
	v_cvt_pk_bf16_f32 v28, v36, v37
	v_cvt_pk_bf16_f32 v29, v38, v39
	v_cvt_pk_bf16_f32 v30, v40, v41
	v_cvt_pk_bf16_f32 v31, v42, v31
	global_load_dwordx4 v[36:39], v[48:49], off
	s_nop 0
	global_store_dwordx4 v[66:67], v[28:31], off offset:256
	s_waitcnt vmcnt(1)
	s_nop 0
	v_lshlrev_b32_e32 v28, 16, v36
	v_and_b32_e32 v29, 0xffff0000, v36
	v_lshlrev_b32_e32 v30, 16, v37
	v_and_b32_e32 v31, 0xffff0000, v37
	v_lshlrev_b32_e32 v36, 16, v38
	v_and_b32_e32 v37, 0xffff0000, v38
	v_lshlrev_b32_e32 v38, 16, v39
	v_and_b32_e32 v39, 0xffff0000, v39
	v_mul_f32_e32 v28, v32, v28
	v_mul_f32_e32 v29, v33, v29
	v_mul_f32_e32 v30, v34, v30
	v_mul_f32_e32 v31, v35, v31
	v_mul_f32_e32 v27, v27, v39
	v_mul_f32_e32 v32, v24, v36
	v_mul_f32_e32 v33, v25, v37
	v_mul_f32_e32 v34, v26, v38
	v_cvt_pk_bf16_f32 v24, v28, v29
	v_cvt_pk_bf16_f32 v25, v30, v31
	v_cvt_pk_bf16_f32 v26, v32, v33
	v_cvt_pk_bf16_f32 v27, v34, v27
	global_load_dwordx4 v[28:31], v[48:49], off offset:256
	v_add_u32_e32 v32, 0xb0, v146
	v_ashrrev_i32_e32 v33, 31, v32
	v_lshlrev_b64 v[32:33], 11, v[32:33]
	v_lshl_add_u64 v[32:33], s[4:5], 0, v[32:33]
	global_store_dwordx4 v[48:49], v[24:27], off
	v_lshl_add_u64 v[32:33], v[32:33], 0, v[148:149]
	s_mov_b64 s[4:5], -1
	s_waitcnt vmcnt(1)
	v_lshlrev_b32_e32 v24, 16, v28
	v_and_b32_e32 v25, 0xffff0000, v28
	v_lshlrev_b32_e32 v26, 16, v29
	v_and_b32_e32 v27, 0xffff0000, v29
	v_lshlrev_b32_e32 v28, 16, v30
	v_and_b32_e32 v29, 0xffff0000, v30
	v_lshlrev_b32_e32 v30, 16, v31
	v_and_b32_e32 v31, 0xffff0000, v31
	v_mul_f32_e32 v20, v20, v24
	v_mul_f32_e32 v21, v21, v25
	v_mul_f32_e32 v22, v22, v26
	v_mul_f32_e32 v23, v23, v27
	v_mul_f32_e32 v15, v15, v31
	v_mul_f32_e32 v24, v12, v28
	v_mul_f32_e32 v25, v13, v29
	v_mul_f32_e32 v26, v14, v30
	v_cvt_pk_bf16_f32 v12, v20, v21
	v_cvt_pk_bf16_f32 v13, v22, v23
	v_cvt_pk_bf16_f32 v14, v24, v25
	v_cvt_pk_bf16_f32 v15, v26, v15
	global_load_dwordx4 v[20:23], v[32:33], off
	s_nop 0
	global_store_dwordx4 v[48:49], v[12:15], off offset:256
	s_waitcnt vmcnt(1)
	s_nop 0
	v_lshlrev_b32_e32 v12, 16, v20
	v_and_b32_e32 v13, 0xffff0000, v20
	v_lshlrev_b32_e32 v14, 16, v21
	v_and_b32_e32 v15, 0xffff0000, v21
	v_lshlrev_b32_e32 v20, 16, v22
	v_and_b32_e32 v21, 0xffff0000, v22
	v_lshlrev_b32_e32 v22, 16, v23
	v_and_b32_e32 v23, 0xffff0000, v23
	v_mul_f32_e32 v12, v16, v12
	v_mul_f32_e32 v13, v17, v13
	v_mul_f32_e32 v14, v18, v14
	v_mul_f32_e32 v15, v19, v15
	v_mul_f32_e32 v11, v11, v23
	v_mul_f32_e32 v16, v8, v20
	v_mul_f32_e32 v17, v9, v21
	v_mul_f32_e32 v18, v10, v22
	v_cvt_pk_bf16_f32 v8, v12, v13
	v_cvt_pk_bf16_f32 v9, v14, v15
	v_cvt_pk_bf16_f32 v10, v16, v17
	v_cvt_pk_bf16_f32 v11, v18, v11
	global_load_dwordx4 v[12:15], v[32:33], off offset:256
	s_nop 0
	global_store_dwordx4 v[32:33], v[8:11], off
	s_waitcnt vmcnt(1)
	s_nop 0
	v_lshlrev_b32_e32 v8, 16, v12
	v_and_b32_e32 v9, 0xffff0000, v12
	v_lshlrev_b32_e32 v10, 16, v13
	v_and_b32_e32 v11, 0xffff0000, v13
	v_lshlrev_b32_e32 v12, 16, v14
	v_and_b32_e32 v13, 0xffff0000, v14
	v_lshlrev_b32_e32 v14, 16, v15
	v_and_b32_e32 v15, 0xffff0000, v15
	v_mul_f32_e32 v3, v3, v15
	v_mul_f32_e32 v4, v4, v8
	v_mul_f32_e32 v5, v5, v9
	v_mul_f32_e32 v6, v6, v10
	v_mul_f32_e32 v7, v7, v11
	v_mul_f32_e32 v8, v0, v12
	v_mul_f32_e32 v9, v1, v13
	v_mul_f32_e32 v10, v2, v14
	v_cvt_pk_bf16_f32 v0, v4, v5
	v_cvt_pk_bf16_f32 v1, v6, v7
	v_cvt_pk_bf16_f32 v2, v8, v9
	v_cvt_pk_bf16_f32 v3, v10, v3
	global_store_dwordx4 v[32:33], v[0:3], off offset:256
.Lho_done:
	s_cbranch_vccnz .LBB0_216
	s_andn2_b64 vcc, exec, s[0:1]
	s_cbranch_vccnz .LBB0_215
	s_barrier
	s_branch .LBB0_215
.LBB0_230:
	s_waitcnt vmcnt(0)
	v_readlane_b32 s50, v255, 28
	v_readlane_b32 s51, v255, 29
	v_readlane_b32 s18, v254, 59
	v_readlane_b32 s51, v255, 34
	v_readlane_b32 s19, v254, 60
	s_brev_b32 s3, 64
	s_barrier

.LBB0_247:
	v_readlane_b32 s4, v250, 25
	v_mbcnt_lo_u32_b32 v138, -1, 0
	v_mbcnt_hi_u32_b32 v138, -1, v138
	s_nop 1
	s_lshr_b32 s5, s4, 8
	s_bfe_u32 s4, s4, 0x20006
	v_and_b32_e32 v139, 15, v138
	v_lshrrev_b32_e32 v146, 4, v138
	s_lshl_b32 s5, s5, 6
	s_lshl_b32 s98, s10, 8
	s_add_u32 s5, s5, s98
	v_add_u32_e32 v139, s5, v139
	v_lshlrev_b32_e32 v228, 11, v139
	v_lshl_add_u32 v228, v146, 4, v228
	s_lshl_b32 s4, s4, 6
	v_add_u32_e32 v228, s4, v228
	v_mov_b32_e32 v229, v228
	v_readlane_b32 s98, v253, 38
	v_readlane_b32 s99, v253, 39
	s_lshl_b32 s4, s3, 9
	s_nop 1
	s_add_u32 s98, s98, s4
	s_addc_u32 s99, s99, 0
	s_add_u32 s100, s98, 0x2000000
	s_addc_u32 s101, s99, 0
	global_load_dwordx4 v[184:187], v228, s[98:99]
	global_load_dwordx4 v[188:191], v228, s[100:101]
	global_load_dwordx4 v[192:195], v228, s[98:99] offset:256
	global_load_dwordx4 v[196:199], v228, s[100:101] offset:256
	v_add_u32_e32 v228, 0x8000, v228
	global_load_dwordx4 v[200:203], v228, s[98:99]
	global_load_dwordx4 v[204:207], v228, s[100:101]
	global_load_dwordx4 v[208:211], v228, s[98:99] offset:256
	global_load_dwordx4 v[212:215], v228, s[100:101] offset:256
	v_add_u32_e32 v228, 0x8000, v228
	global_load_dwordx4 v[216:219], v228, s[98:99]
	global_load_dwordx4 v[220:223], v228, s[100:101]
	global_load_dwordx4 v[224:227], v228, s[98:99] offset:256
	global_load_dwordx4 v[154:157], v228, s[100:101] offset:256
	v_add_u32_e32 v228, 0x8000, v228
	global_load_dwordx4 v[158:161], v228, s[98:99]
	global_load_dwordx4 v[162:165], v228, s[100:101]
	global_load_dwordx4 v[166:169], v228, s[98:99] offset:256
	global_load_dwordx4 v[170:173], v228, s[100:101] offset:256
	v_add_u32_e32 v228, 0x28000, v228
	s_waitcnt vmcnt(14)
	v_lshlrev_b32_e32 v182, 16, v184
	v_and_b32_e32 v183, 0xffff0000, v184
	v_lshlrev_b32_e32 v138, 16, v188
	v_and_b32_e32 v139, 0xffff0000, v188
	v_pk_fma_f32 v[126:127], v[126:127], v[138:139], v[182:183]
	v_lshlrev_b32_e32 v174, 16, v185
	v_and_b32_e32 v175, 0xffff0000, v185
	v_lshlrev_b32_e32 v148, 16, v189
	v_and_b32_e32 v149, 0xffff0000, v189
	v_pk_fma_f32 v[128:129], v[128:129], v[148:149], v[174:175]
	v_lshlrev_b32_e32 v182, 16, v186
	v_and_b32_e32 v183, 0xffff0000, v186
	v_lshlrev_b32_e32 v138, 16, v190
	v_and_b32_e32 v139, 0xffff0000, v190
	v_pk_fma_f32 v[122:123], v[122:123], v[138:139], v[182:183]
	v_lshlrev_b32_e32 v174, 16, v187
	v_and_b32_e32 v175, 0xffff0000, v187
	v_lshlrev_b32_e32 v148, 16, v191
	v_and_b32_e32 v149, 0xffff0000, v191
	v_pk_fma_f32 v[124:125], v[124:125], v[148:149], v[174:175]
	v_cvt_pk_bf16_f32 v126, v126, v127
	v_cvt_pk_bf16_f32 v127, v128, v129
	v_cvt_pk_bf16_f32 v128, v122, v123
	v_cvt_pk_bf16_f32 v129, v124, v125
	global_store_dwordx4 v229, v[126:129], s[98:99]
	s_waitcnt vmcnt(13)
	v_lshlrev_b32_e32 v182, 16, v192
	v_and_b32_e32 v183, 0xffff0000, v192
	v_lshlrev_b32_e32 v138, 16, v196
	v_and_b32_e32 v139, 0xffff0000, v196
	v_pk_fma_f32 v[118:119], v[118:119], v[138:139], v[182:183]
	v_lshlrev_b32_e32 v174, 16, v193
	v_and_b32_e32 v175, 0xffff0000, v193
	v_lshlrev_b32_e32 v148, 16, v197
	v_and_b32_e32 v149, 0xffff0000, v197
	v_pk_fma_f32 v[120:121], v[120:121], v[148:149], v[174:175]
	v_lshlrev_b32_e32 v182, 16, v194
	v_and_b32_e32 v183, 0xffff0000, v194
	v_lshlrev_b32_e32 v138, 16, v198
	v_and_b32_e32 v139, 0xffff0000, v198
	v_pk_fma_f32 v[114:115], v[114:115], v[138:139], v[182:183]
	v_lshlrev_b32_e32 v174, 16, v195
	v_and_b32_e32 v175, 0xffff0000, v195
	v_lshlrev_b32_e32 v148, 16, v199
	v_and_b32_e32 v149, 0xffff0000, v199
	v_pk_fma_f32 v[116:117], v[116:117], v[148:149], v[174:175]
	v_cvt_pk_bf16_f32 v118, v118, v119
	v_cvt_pk_bf16_f32 v119, v120, v121
	v_cvt_pk_bf16_f32 v120, v114, v115
	v_cvt_pk_bf16_f32 v121, v116, v117
	global_store_dwordx4 v229, v[118:121], s[98:99] offset:256
	v_add_u32_e32 v229, 0x8000, v229
	global_load_dwordx4 v[184:187], v228, s[98:99]
	global_load_dwordx4 v[188:191], v228, s[100:101]
	global_load_dwordx4 v[192:195], v228, s[98:99] offset:256
	global_load_dwordx4 v[196:199], v228, s[100:101] offset:256
	v_add_u32_e32 v228, 0x8000, v228
	s_waitcnt vmcnt(16)
	v_lshlrev_b32_e32 v182, 16, v200
	v_and_b32_e32 v183, 0xffff0000, v200
	v_lshlrev_b32_e32 v138, 16, v204
	v_and_b32_e32 v139, 0xffff0000, v204
	v_pk_fma_f32 v[110:111], v[110:111], v[138:139], v[182:183]
	v_lshlrev_b32_e32 v174, 16, v201
	v_and_b32_e32 v175, 0xffff0000, v201
	v_lshlrev_b32_e32 v148, 16, v205
	v_and_b32_e32 v149, 0xffff0000, v205
	v_pk_fma_f32 v[112:113], v[112:113], v[148:149], v[174:175]
	v_lshlrev_b32_e32 v182, 16, v202
	v_and_b32_e32 v183, 0xffff0000, v202
	v_lshlrev_b32_e32 v138, 16, v206
	v_and_b32_e32 v139, 0xffff0000, v206
	v_pk_fma_f32 v[106:107], v[106:107], v[138:139], v[182:183]
	v_lshlrev_b32_e32 v174, 16, v203
	v_and_b32_e32 v175, 0xffff0000, v203
	v_lshlrev_b32_e32 v148, 16, v207
	v_and_b32_e32 v149, 0xffff0000, v207
	v_pk_fma_f32 v[108:109], v[108:109], v[148:149], v[174:175]
	v_cvt_pk_bf16_f32 v110, v110, v111
	v_cvt_pk_bf16_f32 v111, v112, v113
	v_cvt_pk_bf16_f32 v112, v106, v107
	v_cvt_pk_bf16_f32 v113, v108, v109
	global_store_dwordx4 v229, v[110:113], s[98:99]
	s_waitcnt vmcnt(15)
	v_lshlrev_b32_e32 v182, 16, v208
	v_and_b32_e32 v183, 0xffff0000, v208
	v_lshlrev_b32_e32 v138, 16, v212
	v_and_b32_e32 v139, 0xffff0000, v212
	v_pk_fma_f32 v[102:103], v[102:103], v[138:139], v[182:183]
	v_lshlrev_b32_e32 v174, 16, v209
	v_and_b32_e32 v175, 0xffff0000, v209
	v_lshlrev_b32_e32 v148, 16, v213
	v_and_b32_e32 v149, 0xffff0000, v213
	v_pk_fma_f32 v[104:105], v[104:105], v[148:149], v[174:175]
	v_lshlrev_b32_e32 v182, 16, v210
	v_and_b32_e32 v183, 0xffff0000, v210
	v_lshlrev_b32_e32 v138, 16, v214
	v_and_b32_e32 v139, 0xffff0000, v214
	v_pk_fma_f32 v[98:99], v[98:99], v[138:139], v[182:183]
	v_lshlrev_b32_e32 v174, 16, v211
	v_and_b32_e32 v175, 0xffff0000, v211
	v_lshlrev_b32_e32 v148, 16, v215
	v_and_b32_e32 v149, 0xffff0000, v215
	v_pk_fma_f32 v[100:101], v[100:101], v[148:149], v[174:175]
	v_cvt_pk_bf16_f32 v102, v102, v103
	v_cvt_pk_bf16_f32 v103, v104, v105
	v_cvt_pk_bf16_f32 v104, v98, v99
	v_cvt_pk_bf16_f32 v105, v100, v101
	global_store_dwordx4 v229, v[102:105], s[98:99] offset:256
	v_add_u32_e32 v229, 0x8000, v229
	global_load_dwordx4 v[200:203], v228, s[98:99]
	global_load_dwordx4 v[204:207], v228, s[100:101]
	global_load_dwordx4 v[208:211], v228, s[98:99] offset:256
	global_load_dwordx4 v[212:215], v228, s[100:101] offset:256
	v_add_u32_e32 v228, 0x8000, v228
	s_waitcnt vmcnt(18)
	v_lshlrev_b32_e32 v182, 16, v216
	v_and_b32_e32 v183, 0xffff0000, v216
	v_lshlrev_b32_e32 v138, 16, v220
	v_and_b32_e32 v139, 0xffff0000, v220
	v_pk_fma_f32 v[94:95], v[94:95], v[138:139], v[182:183]
	v_lshlrev_b32_e32 v174, 16, v217
	v_and_b32_e32 v175, 0xffff0000, v217
	v_lshlrev_b32_e32 v148, 16, v221
	v_and_b32_e32 v149, 0xffff0000, v221
	v_pk_fma_f32 v[96:97], v[96:97], v[148:149], v[174:175]
	v_lshlrev_b32_e32 v182, 16, v218
	v_and_b32_e32 v183, 0xffff0000, v218
	v_lshlrev_b32_e32 v138, 16, v222
	v_and_b32_e32 v139, 0xffff0000, v222
	v_pk_fma_f32 v[90:91], v[90:91], v[138:139], v[182:183]
	v_lshlrev_b32_e32 v174, 16, v219
	v_and_b32_e32 v175, 0xffff0000, v219
	v_lshlrev_b32_e32 v148, 16, v223
	v_and_b32_e32 v149, 0xffff0000, v223
	v_pk_fma_f32 v[92:93], v[92:93], v[148:149], v[174:175]
	v_cvt_pk_bf16_f32 v94, v94, v95
	v_cvt_pk_bf16_f32 v95, v96, v97
	v_cvt_pk_bf16_f32 v96, v90, v91
	v_cvt_pk_bf16_f32 v97, v92, v93
	global_store_dwordx4 v229, v[94:97], s[98:99]
	s_waitcnt vmcnt(17)
	v_lshlrev_b32_e32 v182, 16, v224
	v_and_b32_e32 v183, 0xffff0000, v224
	v_lshlrev_b32_e32 v138, 16, v154
	v_and_b32_e32 v139, 0xffff0000, v154
	v_pk_fma_f32 v[86:87], v[86:87], v[138:139], v[182:183]
	v_lshlrev_b32_e32 v174, 16, v225
	v_and_b32_e32 v175, 0xffff0000, v225
	v_lshlrev_b32_e32 v148, 16, v155
	v_and_b32_e32 v149, 0xffff0000, v155
	v_pk_fma_f32 v[88:89], v[88:89], v[148:149], v[174:175]
	v_lshlrev_b32_e32 v182, 16, v226
	v_and_b32_e32 v183, 0xffff0000, v226
	v_lshlrev_b32_e32 v138, 16, v156
	v_and_b32_e32 v139, 0xffff0000, v156
	v_pk_fma_f32 v[82:83], v[82:83], v[138:139], v[182:183]
	v_lshlrev_b32_e32 v174, 16, v227
	v_and_b32_e32 v175, 0xffff0000, v227
	v_lshlrev_b32_e32 v148, 16, v157
	v_and_b32_e32 v149, 0xffff0000, v157
	v_pk_fma_f32 v[84:85], v[84:85], v[148:149], v[174:175]
	v_cvt_pk_bf16_f32 v86, v86, v87
	v_cvt_pk_bf16_f32 v87, v88, v89
	v_cvt_pk_bf16_f32 v88, v82, v83
	v_cvt_pk_bf16_f32 v89, v84, v85
	global_store_dwordx4 v229, v[86:89], s[98:99] offset:256
	v_add_u32_e32 v229, 0x8000, v229
	global_load_dwordx4 v[216:219], v228, s[98:99]
	global_load_dwordx4 v[220:223], v228, s[100:101]
	global_load_dwordx4 v[224:227], v228, s[98:99] offset:256
	global_load_dwordx4 v[154:157], v228, s[100:101] offset:256
	v_add_u32_e32 v228, 0x8000, v228
	s_waitcnt vmcnt(20)
	v_lshlrev_b32_e32 v182, 16, v158
	v_and_b32_e32 v183, 0xffff0000, v158
	v_lshlrev_b32_e32 v138, 16, v162
	v_and_b32_e32 v139, 0xffff0000, v162
	v_pk_fma_f32 v[78:79], v[78:79], v[138:139], v[182:183]
	v_lshlrev_b32_e32 v174, 16, v159
	v_and_b32_e32 v175, 0xffff0000, v159
	v_lshlrev_b32_e32 v148, 16, v163
	v_and_b32_e32 v149, 0xffff0000, v163
	v_pk_fma_f32 v[80:81], v[80:81], v[148:149], v[174:175]
	v_lshlrev_b32_e32 v182, 16, v160
	v_and_b32_e32 v183, 0xffff0000, v160
	v_lshlrev_b32_e32 v138, 16, v164
	v_and_b32_e32 v139, 0xffff0000, v164
	v_pk_fma_f32 v[74:75], v[74:75], v[138:139], v[182:183]
	v_lshlrev_b32_e32 v174, 16, v161
	v_and_b32_e32 v175, 0xffff0000, v161
	v_lshlrev_b32_e32 v148, 16, v165
	v_and_b32_e32 v149, 0xffff0000, v165
	v_pk_fma_f32 v[76:77], v[76:77], v[148:149], v[174:175]
	v_cvt_pk_bf16_f32 v78, v78, v79
	v_cvt_pk_bf16_f32 v79, v80, v81
	v_cvt_pk_bf16_f32 v80, v74, v75
	v_cvt_pk_bf16_f32 v81, v76, v77
	global_store_dwordx4 v229, v[78:81], s[98:99]
	s_waitcnt vmcnt(19)
	v_lshlrev_b32_e32 v182, 16, v166
	v_and_b32_e32 v183, 0xffff0000, v166
	v_lshlrev_b32_e32 v138, 16, v170
	v_and_b32_e32 v139, 0xffff0000, v170
	v_pk_fma_f32 v[70:71], v[70:71], v[138:139], v[182:183]
	v_lshlrev_b32_e32 v174, 16, v167
	v_and_b32_e32 v175, 0xffff0000, v167
	v_lshlrev_b32_e32 v148, 16, v171
	v_and_b32_e32 v149, 0xffff0000, v171
	v_pk_fma_f32 v[72:73], v[72:73], v[148:149], v[174:175]
	v_lshlrev_b32_e32 v182, 16, v168
	v_and_b32_e32 v183, 0xffff0000, v168
	v_lshlrev_b32_e32 v138, 16, v172
	v_and_b32_e32 v139, 0xffff0000, v172
	v_pk_fma_f32 v[66:67], v[66:67], v[138:139], v[182:183]
	v_lshlrev_b32_e32 v174, 16, v169
	v_and_b32_e32 v175, 0xffff0000, v169
	v_lshlrev_b32_e32 v148, 16, v173
	v_and_b32_e32 v149, 0xffff0000, v173
	v_pk_fma_f32 v[68:69], v[68:69], v[148:149], v[174:175]
	v_cvt_pk_bf16_f32 v70, v70, v71
	v_cvt_pk_bf16_f32 v71, v72, v73
	v_cvt_pk_bf16_f32 v72, v66, v67
	v_cvt_pk_bf16_f32 v73, v68, v69
	global_store_dwordx4 v229, v[70:73], s[98:99] offset:256
	v_add_u32_e32 v229, 0x28000, v229
	global_load_dwordx4 v[158:161], v228, s[98:99]
	global_load_dwordx4 v[162:165], v228, s[100:101]
	global_load_dwordx4 v[166:169], v228, s[98:99] offset:256
	global_load_dwordx4 v[170:173], v228, s[100:101] offset:256
	s_waitcnt vmcnt(20)
	v_lshlrev_b32_e32 v182, 16, v184
	v_and_b32_e32 v183, 0xffff0000, v184
	v_lshlrev_b32_e32 v138, 16, v188
	v_and_b32_e32 v139, 0xffff0000, v188
	v_pk_fma_f32 v[60:61], v[60:61], v[138:139], v[182:183]
	v_lshlrev_b32_e32 v174, 16, v185
	v_and_b32_e32 v175, 0xffff0000, v185
	v_lshlrev_b32_e32 v148, 16, v189
	v_and_b32_e32 v149, 0xffff0000, v189
	v_pk_fma_f32 v[62:63], v[62:63], v[148:149], v[174:175]
	v_lshlrev_b32_e32 v182, 16, v186
	v_and_b32_e32 v183, 0xffff0000, v186
	v_lshlrev_b32_e32 v138, 16, v190
	v_and_b32_e32 v139, 0xffff0000, v190
	v_pk_fma_f32 v[56:57], v[56:57], v[138:139], v[182:183]
	v_lshlrev_b32_e32 v174, 16, v187
	v_and_b32_e32 v175, 0xffff0000, v187
	v_lshlrev_b32_e32 v148, 16, v191
	v_and_b32_e32 v149, 0xffff0000, v191
	v_pk_fma_f32 v[58:59], v[58:59], v[148:149], v[174:175]
	v_cvt_pk_bf16_f32 v60, v60, v61
	v_cvt_pk_bf16_f32 v61, v62, v63
	v_cvt_pk_bf16_f32 v62, v56, v57
	v_cvt_pk_bf16_f32 v63, v58, v59
	global_store_dwordx4 v229, v[60:63], s[98:99]
	s_waitcnt vmcnt(19)
	v_lshlrev_b32_e32 v182, 16, v192
	v_and_b32_e32 v183, 0xffff0000, v192
	v_lshlrev_b32_e32 v138, 16, v196
	v_and_b32_e32 v139, 0xffff0000, v196
	v_pk_fma_f32 v[52:53], v[52:53], v[138:139], v[182:183]
	v_lshlrev_b32_e32 v174, 16, v193
	v_and_b32_e32 v175, 0xffff0000, v193
	v_lshlrev_b32_e32 v148, 16, v197
	v_and_b32_e32 v149, 0xffff0000, v197
	v_pk_fma_f32 v[54:55], v[54:55], v[148:149], v[174:175]
	v_lshlrev_b32_e32 v182, 16, v194
	v_and_b32_e32 v183, 0xffff0000, v194
	v_lshlrev_b32_e32 v138, 16, v198
	v_and_b32_e32 v139, 0xffff0000, v198
	v_pk_fma_f32 v[48:49], v[48:49], v[138:139], v[182:183]
	v_lshlrev_b32_e32 v174, 16, v195
	v_and_b32_e32 v175, 0xffff0000, v195
	v_lshlrev_b32_e32 v148, 16, v199
	v_and_b32_e32 v149, 0xffff0000, v199
	v_pk_fma_f32 v[50:51], v[50:51], v[148:149], v[174:175]
	v_cvt_pk_bf16_f32 v52, v52, v53
	v_cvt_pk_bf16_f32 v53, v54, v55
	v_cvt_pk_bf16_f32 v54, v48, v49
	v_cvt_pk_bf16_f32 v55, v50, v51
	global_store_dwordx4 v229, v[52:55], s[98:99] offset:256
	v_add_u32_e32 v229, 0x8000, v229
	s_waitcnt vmcnt(16)
	v_lshlrev_b32_e32 v182, 16, v200
	v_and_b32_e32 v183, 0xffff0000, v200
	v_lshlrev_b32_e32 v138, 16, v204
	v_and_b32_e32 v139, 0xffff0000, v204
	v_pk_fma_f32 v[44:45], v[44:45], v[138:139], v[182:183]
	v_lshlrev_b32_e32 v174, 16, v201
	v_and_b32_e32 v175, 0xffff0000, v201
	v_lshlrev_b32_e32 v148, 16, v205
	v_and_b32_e32 v149, 0xffff0000, v205
	v_pk_fma_f32 v[46:47], v[46:47], v[148:149], v[174:175]
	v_lshlrev_b32_e32 v182, 16, v202
	v_and_b32_e32 v183, 0xffff0000, v202
	v_lshlrev_b32_e32 v138, 16, v206
	v_and_b32_e32 v139, 0xffff0000, v206
	v_pk_fma_f32 v[40:41], v[40:41], v[138:139], v[182:183]
	v_lshlrev_b32_e32 v174, 16, v203
	v_and_b32_e32 v175, 0xffff0000, v203
	v_lshlrev_b32_e32 v148, 16, v207
	v_and_b32_e32 v149, 0xffff0000, v207
	v_pk_fma_f32 v[42:43], v[42:43], v[148:149], v[174:175]
	v_cvt_pk_bf16_f32 v44, v44, v45
	v_cvt_pk_bf16_f32 v45, v46, v47
	v_cvt_pk_bf16_f32 v46, v40, v41
	v_cvt_pk_bf16_f32 v47, v42, v43
	global_store_dwordx4 v229, v[44:47], s[98:99]
	s_waitcnt vmcnt(15)
	v_lshlrev_b32_e32 v182, 16, v208
	v_and_b32_e32 v183, 0xffff0000, v208
	v_lshlrev_b32_e32 v138, 16, v212
	v_and_b32_e32 v139, 0xffff0000, v212
	v_pk_fma_f32 v[36:37], v[36:37], v[138:139], v[182:183]
	v_lshlrev_b32_e32 v174, 16, v209
	v_and_b32_e32 v175, 0xffff0000, v209
	v_lshlrev_b32_e32 v148, 16, v213
	v_and_b32_e32 v149, 0xffff0000, v213
	v_pk_fma_f32 v[38:39], v[38:39], v[148:149], v[174:175]
	v_lshlrev_b32_e32 v182, 16, v210
	v_and_b32_e32 v183, 0xffff0000, v210
	v_lshlrev_b32_e32 v138, 16, v214
	v_and_b32_e32 v139, 0xffff0000, v214
	v_pk_fma_f32 v[32:33], v[32:33], v[138:139], v[182:183]
	v_lshlrev_b32_e32 v174, 16, v211
	v_and_b32_e32 v175, 0xffff0000, v211
	v_lshlrev_b32_e32 v148, 16, v215
	v_and_b32_e32 v149, 0xffff0000, v215
	v_pk_fma_f32 v[34:35], v[34:35], v[148:149], v[174:175]
	v_cvt_pk_bf16_f32 v36, v36, v37
	v_cvt_pk_bf16_f32 v37, v38, v39
	v_cvt_pk_bf16_f32 v38, v32, v33
	v_cvt_pk_bf16_f32 v39, v34, v35
	global_store_dwordx4 v229, v[36:39], s[98:99] offset:256
	v_add_u32_e32 v229, 0x8000, v229
	s_waitcnt vmcnt(12)
	v_lshlrev_b32_e32 v182, 16, v216
	v_and_b32_e32 v183, 0xffff0000, v216
	v_lshlrev_b32_e32 v138, 16, v220
	v_and_b32_e32 v139, 0xffff0000, v220
	v_pk_fma_f32 v[28:29], v[28:29], v[138:139], v[182:183]
	v_lshlrev_b32_e32 v174, 16, v217
	v_and_b32_e32 v175, 0xffff0000, v217
	v_lshlrev_b32_e32 v148, 16, v221
	v_and_b32_e32 v149, 0xffff0000, v221
	v_pk_fma_f32 v[30:31], v[30:31], v[148:149], v[174:175]
	v_lshlrev_b32_e32 v182, 16, v218
	v_and_b32_e32 v183, 0xffff0000, v218
	v_lshlrev_b32_e32 v138, 16, v222
	v_and_b32_e32 v139, 0xffff0000, v222
	v_pk_fma_f32 v[24:25], v[24:25], v[138:139], v[182:183]
	v_lshlrev_b32_e32 v174, 16, v219
	v_and_b32_e32 v175, 0xffff0000, v219
	v_lshlrev_b32_e32 v148, 16, v223
	v_and_b32_e32 v149, 0xffff0000, v223
	v_pk_fma_f32 v[26:27], v[26:27], v[148:149], v[174:175]
	v_cvt_pk_bf16_f32 v28, v28, v29
	v_cvt_pk_bf16_f32 v29, v30, v31
	v_cvt_pk_bf16_f32 v30, v24, v25
	v_cvt_pk_bf16_f32 v31, v26, v27
	global_store_dwordx4 v229, v[28:31], s[98:99]
	s_waitcnt vmcnt(11)
	v_lshlrev_b32_e32 v182, 16, v224
	v_and_b32_e32 v183, 0xffff0000, v224
	v_lshlrev_b32_e32 v138, 16, v154
	v_and_b32_e32 v139, 0xffff0000, v154
	v_pk_fma_f32 v[20:21], v[20:21], v[138:139], v[182:183]
	v_lshlrev_b32_e32 v174, 16, v225
	v_and_b32_e32 v175, 0xffff0000, v225
	v_lshlrev_b32_e32 v148, 16, v155
	v_and_b32_e32 v149, 0xffff0000, v155
	v_pk_fma_f32 v[22:23], v[22:23], v[148:149], v[174:175]
	v_lshlrev_b32_e32 v182, 16, v226
	v_and_b32_e32 v183, 0xffff0000, v226
	v_lshlrev_b32_e32 v138, 16, v156
	v_and_b32_e32 v139, 0xffff0000, v156
	v_pk_fma_f32 v[16:17], v[16:17], v[138:139], v[182:183]
	v_lshlrev_b32_e32 v174, 16, v227
	v_and_b32_e32 v175, 0xffff0000, v227
	v_lshlrev_b32_e32 v148, 16, v157
	v_and_b32_e32 v149, 0xffff0000, v157
	v_pk_fma_f32 v[18:19], v[18:19], v[148:149], v[174:175]
	v_cvt_pk_bf16_f32 v20, v20, v21
	v_cvt_pk_bf16_f32 v21, v22, v23
	v_cvt_pk_bf16_f32 v22, v16, v17
	v_cvt_pk_bf16_f32 v23, v18, v19
	global_store_dwordx4 v229, v[20:23], s[98:99] offset:256
	v_add_u32_e32 v229, 0x8000, v229
	s_waitcnt vmcnt(8)
	v_lshlrev_b32_e32 v182, 16, v158
	v_and_b32_e32 v183, 0xffff0000, v158
	v_lshlrev_b32_e32 v138, 16, v162
	v_and_b32_e32 v139, 0xffff0000, v162
	v_pk_fma_f32 v[12:13], v[12:13], v[138:139], v[182:183]
	v_lshlrev_b32_e32 v174, 16, v159
	v_and_b32_e32 v175, 0xffff0000, v159
	v_lshlrev_b32_e32 v148, 16, v163
	v_and_b32_e32 v149, 0xffff0000, v163
	v_pk_fma_f32 v[14:15], v[14:15], v[148:149], v[174:175]
	v_lshlrev_b32_e32 v182, 16, v160
	v_and_b32_e32 v183, 0xffff0000, v160
	v_lshlrev_b32_e32 v138, 16, v164
	v_and_b32_e32 v139, 0xffff0000, v164
	v_pk_fma_f32 v[8:9], v[8:9], v[138:139], v[182:183]
	v_lshlrev_b32_e32 v174, 16, v161
	v_and_b32_e32 v175, 0xffff0000, v161
	v_lshlrev_b32_e32 v148, 16, v165
	v_and_b32_e32 v149, 0xffff0000, v165
	v_pk_fma_f32 v[10:11], v[10:11], v[148:149], v[174:175]
	v_cvt_pk_bf16_f32 v12, v12, v13
	v_cvt_pk_bf16_f32 v13, v14, v15
	v_cvt_pk_bf16_f32 v14, v8, v9
	v_cvt_pk_bf16_f32 v15, v10, v11
	global_store_dwordx4 v229, v[12:15], s[98:99]
	s_waitcnt vmcnt(7)
	v_lshlrev_b32_e32 v182, 16, v166
	v_and_b32_e32 v183, 0xffff0000, v166
	v_lshlrev_b32_e32 v138, 16, v170
	v_and_b32_e32 v139, 0xffff0000, v170
	v_pk_fma_f32 v[4:5], v[4:5], v[138:139], v[182:183]
	v_lshlrev_b32_e32 v174, 16, v167
	v_and_b32_e32 v175, 0xffff0000, v167
	v_lshlrev_b32_e32 v148, 16, v171
	v_and_b32_e32 v149, 0xffff0000, v171
	v_pk_fma_f32 v[6:7], v[6:7], v[148:149], v[174:175]
	v_lshlrev_b32_e32 v182, 16, v168
	v_and_b32_e32 v183, 0xffff0000, v168
	v_lshlrev_b32_e32 v138, 16, v172
	v_and_b32_e32 v139, 0xffff0000, v172
	v_pk_fma_f32 v[0:1], v[0:1], v[138:139], v[182:183]
	v_lshlrev_b32_e32 v174, 16, v169
	v_and_b32_e32 v175, 0xffff0000, v169
	v_lshlrev_b32_e32 v148, 16, v173
	v_and_b32_e32 v149, 0xffff0000, v173
	v_pk_fma_f32 v[2:3], v[2:3], v[148:149], v[174:175]
	v_cvt_pk_bf16_f32 v4, v4, v5
	v_cvt_pk_bf16_f32 v5, v6, v7
	v_cvt_pk_bf16_f32 v6, v0, v1
	v_cvt_pk_bf16_f32 v7, v2, v3
	global_store_dwordx4 v229, v[4:7], s[98:99] offset:256
	s_brev_b32 s3, 64
	v_readlane_b32 s50, v255, 28
	v_readlane_b32 s51, v255, 29
	s_mov_b64 s[4:5], -1
	s_andn2_b64 vcc, exec, s[38:39]
	s_branch .Lao_done
	v_lshl_add_u32 v146, s10, 8, v65
	v_lshl_or_b32 v148, s3, 8, v151
	v_ashrrev_i32_e32 v147, 31, v146
	v_readlane_b32 s4, v253, 38
	v_lshlrev_b64 v[154:155], 11, v[146:147]
	v_readlane_b32 s5, v253, 39
	v_ashrrev_i32_e32 v149, 31, v148
	v_lshlrev_b64 v[148:149], 1, v[148:149]
	v_lshl_add_u64 v[154:155], s[4:5], 0, v[154:155]
	v_lshl_add_u64 v[162:163], v[154:155], 0, v[148:149]
	v_add_co_u32_e32 v164, vcc, 0x2000000, v162
	global_load_dwordx4 v[154:157], v[162:163], off
	s_nop 0
	v_addc_co_u32_e32 v165, vcc, 0, v163, vcc
	global_load_dwordx4 v[158:161], v[164:165], off
	s_brev_b32 s3, 64
	v_readlane_b32 s50, v255, 28
	v_readlane_b32 s51, v255, 29
	s_waitcnt vmcnt(0)
	v_lshlrev_b32_e32 v138, 16, v154
	v_lshlrev_b32_e32 v147, 16, v157
	v_and_b32_e32 v153, 0xffff0000, v157
	v_lshlrev_b32_e32 v139, 16, v158
	v_fmac_f32_e32 v138, v126, v139
	v_and_b32_e32 v126, 0xffff0000, v154
	v_and_b32_e32 v139, 0xffff0000, v158
	v_fmac_f32_e32 v126, v127, v139
	v_lshlrev_b32_e32 v127, 16, v155
	v_lshlrev_b32_e32 v139, 16, v159
	v_fmac_f32_e32 v127, v128, v139
	v_and_b32_e32 v128, 0xffff0000, v155
	v_and_b32_e32 v139, 0xffff0000, v159
	v_fmac_f32_e32 v128, v129, v139
	v_lshlrev_b32_e32 v129, 16, v156
	v_lshlrev_b32_e32 v139, 16, v160
	v_fmac_f32_e32 v129, v122, v139
	v_and_b32_e32 v139, 0xffff0000, v156
	v_and_b32_e32 v122, 0xffff0000, v160
	v_fmac_f32_e32 v139, v123, v122
	v_lshlrev_b32_e32 v122, 16, v161
	v_fmac_f32_e32 v147, v124, v122
	v_and_b32_e32 v122, 0xffff0000, v161
	v_fmac_f32_e32 v153, v125, v122
	v_cvt_pk_bf16_f32 v122, v138, v126
	v_cvt_pk_bf16_f32 v123, v127, v128
	v_cvt_pk_bf16_f32 v124, v129, v139
	v_cvt_pk_bf16_f32 v125, v147, v153
	global_store_dwordx4 v[162:163], v[122:125], off
	global_load_dwordx4 v[122:125], v[162:163], off offset:256
	s_nop 0
	global_load_dwordx4 v[126:129], v[164:165], off offset:256
	s_waitcnt vmcnt(1)
	v_lshlrev_b32_e32 v138, 16, v122
	s_waitcnt vmcnt(0)
	v_lshlrev_b32_e32 v139, 16, v126
	v_fmac_f32_e32 v138, v118, v139
	v_and_b32_e32 v118, 0xffff0000, v122
	v_and_b32_e32 v122, 0xffff0000, v126
	v_fmac_f32_e32 v118, v119, v122
	v_lshlrev_b32_e32 v119, 16, v123
	v_lshlrev_b32_e32 v122, 16, v127
	v_fmac_f32_e32 v119, v120, v122
	v_and_b32_e32 v120, 0xffff0000, v123
	v_and_b32_e32 v122, 0xffff0000, v127
	v_fmac_f32_e32 v120, v121, v122
	v_lshlrev_b32_e32 v121, 16, v124
	v_lshlrev_b32_e32 v122, 16, v128
	v_fmac_f32_e32 v121, v114, v122
	v_and_b32_e32 v122, 0xffff0000, v124
	v_and_b32_e32 v114, 0xffff0000, v128
	v_fmac_f32_e32 v122, v115, v114
	v_lshlrev_b32_e32 v123, 16, v125
	v_lshlrev_b32_e32 v114, 16, v129
	v_fmac_f32_e32 v123, v116, v114
	v_and_b32_e32 v124, 0xffff0000, v125
	v_and_b32_e32 v114, 0xffff0000, v129
	v_fmac_f32_e32 v124, v117, v114
	v_cvt_pk_bf16_f32 v114, v138, v118
	v_cvt_pk_bf16_f32 v115, v119, v120
	v_cvt_pk_bf16_f32 v116, v121, v122
	v_cvt_pk_bf16_f32 v117, v123, v124
	global_store_dwordx4 v[162:163], v[114:117], off offset:256
	s_nop 1
	v_or_b32_e32 v114, 16, v146
	v_ashrrev_i32_e32 v115, 31, v114
	v_lshlrev_b64 v[114:115], 11, v[114:115]
	v_lshl_add_u64 v[114:115], s[4:5], 0, v[114:115]
	v_lshl_add_u64 v[114:115], v[114:115], 0, v[148:149]
	v_add_co_u32_e32 v124, vcc, s3, v114
	global_load_dwordx4 v[116:119], v[114:115], off
	s_nop 0
	v_addc_co_u32_e32 v125, vcc, 0, v115, vcc
	global_load_dwordx4 v[120:123], v[124:125], off
	s_waitcnt vmcnt(1)
	v_lshlrev_b32_e32 v126, 16, v116
	s_waitcnt vmcnt(0)
	v_lshlrev_b32_e32 v127, 16, v120
	v_fmac_f32_e32 v126, v110, v127
	v_and_b32_e32 v110, 0xffff0000, v116
	v_and_b32_e32 v116, 0xffff0000, v120
	v_fmac_f32_e32 v110, v111, v116
	v_lshlrev_b32_e32 v111, 16, v117
	v_lshlrev_b32_e32 v116, 16, v121
	v_fmac_f32_e32 v111, v112, v116
	v_and_b32_e32 v112, 0xffff0000, v117
	v_and_b32_e32 v116, 0xffff0000, v121
	v_fmac_f32_e32 v112, v113, v116
	v_lshlrev_b32_e32 v113, 16, v118
	v_lshlrev_b32_e32 v116, 16, v122
	v_fmac_f32_e32 v113, v106, v116
	v_and_b32_e32 v116, 0xffff0000, v118
	v_and_b32_e32 v106, 0xffff0000, v122
	v_fmac_f32_e32 v116, v107, v106
	v_lshlrev_b32_e32 v117, 16, v119
	v_lshlrev_b32_e32 v106, 16, v123
	v_fmac_f32_e32 v117, v108, v106
	v_and_b32_e32 v118, 0xffff0000, v119
	v_and_b32_e32 v106, 0xffff0000, v123
	v_fmac_f32_e32 v118, v109, v106
	v_cvt_pk_bf16_f32 v106, v126, v110
	v_cvt_pk_bf16_f32 v107, v111, v112
	v_cvt_pk_bf16_f32 v108, v113, v116
	v_cvt_pk_bf16_f32 v109, v117, v118
	global_store_dwordx4 v[114:115], v[106:109], off
	global_load_dwordx4 v[106:109], v[114:115], off offset:256
	s_nop 0
	global_load_dwordx4 v[110:113], v[124:125], off offset:256
	s_waitcnt vmcnt(1)
	v_lshlrev_b32_e32 v116, 16, v106
	s_waitcnt vmcnt(0)
	v_lshlrev_b32_e32 v117, 16, v110
	v_fmac_f32_e32 v116, v102, v117
	v_and_b32_e32 v102, 0xffff0000, v106
	v_and_b32_e32 v106, 0xffff0000, v110
	v_fmac_f32_e32 v102, v103, v106
	v_lshlrev_b32_e32 v103, 16, v107
	v_lshlrev_b32_e32 v106, 16, v111
	v_fmac_f32_e32 v103, v104, v106
	v_and_b32_e32 v104, 0xffff0000, v107
	v_and_b32_e32 v106, 0xffff0000, v111
	v_fmac_f32_e32 v104, v105, v106
	v_lshlrev_b32_e32 v105, 16, v108
	v_lshlrev_b32_e32 v106, 16, v112
	v_fmac_f32_e32 v105, v98, v106
	v_and_b32_e32 v106, 0xffff0000, v108
	v_and_b32_e32 v98, 0xffff0000, v112
	v_fmac_f32_e32 v106, v99, v98
	v_lshlrev_b32_e32 v107, 16, v109
	v_lshlrev_b32_e32 v98, 16, v113
	v_fmac_f32_e32 v107, v100, v98
	v_and_b32_e32 v108, 0xffff0000, v109
	v_and_b32_e32 v98, 0xffff0000, v113
	v_fmac_f32_e32 v108, v101, v98
	v_cvt_pk_bf16_f32 v98, v116, v102
	v_cvt_pk_bf16_f32 v99, v103, v104
	v_cvt_pk_bf16_f32 v100, v105, v106
	v_cvt_pk_bf16_f32 v101, v107, v108
	global_store_dwordx4 v[114:115], v[98:101], off offset:256
	s_nop 1
	v_or_b32_e32 v98, 32, v146
	v_ashrrev_i32_e32 v99, 31, v98
	v_lshlrev_b64 v[98:99], 11, v[98:99]
	v_lshl_add_u64 v[98:99], s[4:5], 0, v[98:99]
	v_lshl_add_u64 v[98:99], v[98:99], 0, v[148:149]
	v_add_co_u32_e32 v108, vcc, s3, v98
	global_load_dwordx4 v[100:103], v[98:99], off
	s_nop 0
	v_addc_co_u32_e32 v109, vcc, 0, v99, vcc
	global_load_dwordx4 v[104:107], v[108:109], off
	s_waitcnt vmcnt(1)
	v_lshlrev_b32_e32 v110, 16, v100
	s_waitcnt vmcnt(0)
	v_lshlrev_b32_e32 v111, 16, v104
	v_fmac_f32_e32 v110, v94, v111
	v_and_b32_e32 v94, 0xffff0000, v100
	v_and_b32_e32 v100, 0xffff0000, v104
	v_fmac_f32_e32 v94, v95, v100
	v_lshlrev_b32_e32 v95, 16, v101
	v_lshlrev_b32_e32 v100, 16, v105
	v_fmac_f32_e32 v95, v96, v100
	v_and_b32_e32 v96, 0xffff0000, v101
	v_and_b32_e32 v100, 0xffff0000, v105
	v_fmac_f32_e32 v96, v97, v100
	v_lshlrev_b32_e32 v97, 16, v102
	v_lshlrev_b32_e32 v100, 16, v106
	v_fmac_f32_e32 v97, v90, v100
	v_and_b32_e32 v100, 0xffff0000, v102
	v_and_b32_e32 v90, 0xffff0000, v106
	v_fmac_f32_e32 v100, v91, v90
	v_lshlrev_b32_e32 v101, 16, v103
	v_lshlrev_b32_e32 v90, 16, v107
	v_fmac_f32_e32 v101, v92, v90
	v_and_b32_e32 v102, 0xffff0000, v103
	v_and_b32_e32 v90, 0xffff0000, v107
	v_fmac_f32_e32 v102, v93, v90
	v_cvt_pk_bf16_f32 v90, v110, v94
	v_cvt_pk_bf16_f32 v91, v95, v96
	v_cvt_pk_bf16_f32 v92, v97, v100
	v_cvt_pk_bf16_f32 v93, v101, v102
	global_store_dwordx4 v[98:99], v[90:93], off
	global_load_dwordx4 v[90:93], v[98:99], off offset:256
	s_nop 0
	global_load_dwordx4 v[94:97], v[108:109], off offset:256
	s_waitcnt vmcnt(1)
	v_lshlrev_b32_e32 v100, 16, v90
	s_waitcnt vmcnt(0)
	v_lshlrev_b32_e32 v101, 16, v94
	v_fmac_f32_e32 v100, v86, v101
	v_and_b32_e32 v86, 0xffff0000, v90
	v_and_b32_e32 v90, 0xffff0000, v94
	v_fmac_f32_e32 v86, v87, v90
	v_lshlrev_b32_e32 v87, 16, v91
	v_lshlrev_b32_e32 v90, 16, v95
	v_fmac_f32_e32 v87, v88, v90
	v_and_b32_e32 v88, 0xffff0000, v91
	v_and_b32_e32 v90, 0xffff0000, v95
	v_fmac_f32_e32 v88, v89, v90
	v_lshlrev_b32_e32 v89, 16, v92
	v_lshlrev_b32_e32 v90, 16, v96
	v_fmac_f32_e32 v89, v82, v90
	v_and_b32_e32 v90, 0xffff0000, v92
	v_and_b32_e32 v82, 0xffff0000, v96
	v_fmac_f32_e32 v90, v83, v82
	v_lshlrev_b32_e32 v91, 16, v93
	v_lshlrev_b32_e32 v82, 16, v97
	v_fmac_f32_e32 v91, v84, v82
	v_and_b32_e32 v92, 0xffff0000, v93
	v_and_b32_e32 v82, 0xffff0000, v97
	v_fmac_f32_e32 v92, v85, v82
	v_cvt_pk_bf16_f32 v82, v100, v86
	v_cvt_pk_bf16_f32 v83, v87, v88
	v_cvt_pk_bf16_f32 v84, v89, v90
	v_cvt_pk_bf16_f32 v85, v91, v92
	global_store_dwordx4 v[98:99], v[82:85], off offset:256
	s_nop 1
	v_or_b32_e32 v82, 48, v146
	v_ashrrev_i32_e32 v83, 31, v82
	v_lshlrev_b64 v[82:83], 11, v[82:83]
	v_lshl_add_u64 v[82:83], s[4:5], 0, v[82:83]
	v_lshl_add_u64 v[82:83], v[82:83], 0, v[148:149]
	v_add_co_u32_e32 v92, vcc, s3, v82
	global_load_dwordx4 v[84:87], v[82:83], off
	s_nop 0
	v_addc_co_u32_e32 v93, vcc, 0, v83, vcc
	global_load_dwordx4 v[88:91], v[92:93], off
	s_waitcnt vmcnt(1)
	v_lshlrev_b32_e32 v94, 16, v84
	s_waitcnt vmcnt(0)
	v_lshlrev_b32_e32 v95, 16, v88
	v_fmac_f32_e32 v94, v78, v95
	v_and_b32_e32 v78, 0xffff0000, v84
	v_and_b32_e32 v84, 0xffff0000, v88
	v_fmac_f32_e32 v78, v79, v84
	v_lshlrev_b32_e32 v79, 16, v85
	v_lshlrev_b32_e32 v84, 16, v89
	v_fmac_f32_e32 v79, v80, v84
	v_and_b32_e32 v80, 0xffff0000, v85
	v_and_b32_e32 v84, 0xffff0000, v89
	v_fmac_f32_e32 v80, v81, v84
	v_lshlrev_b32_e32 v81, 16, v86
	v_lshlrev_b32_e32 v84, 16, v90
	v_fmac_f32_e32 v81, v74, v84
	v_and_b32_e32 v84, 0xffff0000, v86
	v_and_b32_e32 v74, 0xffff0000, v90
	v_fmac_f32_e32 v84, v75, v74
	v_lshlrev_b32_e32 v85, 16, v87
	v_lshlrev_b32_e32 v74, 16, v91
	v_fmac_f32_e32 v85, v76, v74
	v_and_b32_e32 v86, 0xffff0000, v87
	v_and_b32_e32 v74, 0xffff0000, v91
	v_fmac_f32_e32 v86, v77, v74
	v_cvt_pk_bf16_f32 v74, v94, v78
	v_cvt_pk_bf16_f32 v75, v79, v80
	v_cvt_pk_bf16_f32 v76, v81, v84
	v_cvt_pk_bf16_f32 v77, v85, v86
	global_store_dwordx4 v[82:83], v[74:77], off
	global_load_dwordx4 v[74:77], v[82:83], off offset:256
	s_nop 0
	global_load_dwordx4 v[78:81], v[92:93], off offset:256
	s_waitcnt vmcnt(1)
	v_lshlrev_b32_e32 v84, 16, v74
	s_waitcnt vmcnt(0)
	v_lshlrev_b32_e32 v85, 16, v78
	v_fmac_f32_e32 v84, v70, v85
	v_and_b32_e32 v70, 0xffff0000, v74
	v_and_b32_e32 v74, 0xffff0000, v78
	v_fmac_f32_e32 v70, v71, v74
	v_lshlrev_b32_e32 v71, 16, v75
	v_lshlrev_b32_e32 v74, 16, v79
	v_fmac_f32_e32 v71, v72, v74
	v_and_b32_e32 v72, 0xffff0000, v75
	v_and_b32_e32 v74, 0xffff0000, v79
	v_fmac_f32_e32 v72, v73, v74
	v_lshlrev_b32_e32 v73, 16, v76
	v_lshlrev_b32_e32 v74, 16, v80
	v_fmac_f32_e32 v73, v66, v74
	v_and_b32_e32 v74, 0xffff0000, v76
	v_and_b32_e32 v66, 0xffff0000, v80
	v_fmac_f32_e32 v74, v67, v66
	v_lshlrev_b32_e32 v75, 16, v77
	v_lshlrev_b32_e32 v66, 16, v81
	v_fmac_f32_e32 v75, v68, v66
	v_and_b32_e32 v76, 0xffff0000, v77
	v_and_b32_e32 v66, 0xffff0000, v81
	v_fmac_f32_e32 v76, v69, v66
	v_cvt_pk_bf16_f32 v66, v84, v70
	v_cvt_pk_bf16_f32 v67, v71, v72
	v_cvt_pk_bf16_f32 v68, v73, v74
	v_cvt_pk_bf16_f32 v69, v75, v76
	global_store_dwordx4 v[82:83], v[66:69], off offset:256
	s_nop 1
	v_add_u32_e32 v66, 0x80, v146
	v_ashrrev_i32_e32 v67, 31, v66
	v_lshlrev_b64 v[66:67], 11, v[66:67]
	v_lshl_add_u64 v[66:67], s[4:5], 0, v[66:67]
	v_lshl_add_u64 v[66:67], v[66:67], 0, v[148:149]
	v_add_co_u32_e32 v76, vcc, s3, v66
	global_load_dwordx4 v[68:71], v[66:67], off
	s_nop 0
	v_addc_co_u32_e32 v77, vcc, 0, v67, vcc
	global_load_dwordx4 v[72:75], v[76:77], off
	s_waitcnt vmcnt(1)
	v_lshlrev_b32_e32 v78, 16, v68
	s_waitcnt vmcnt(0)
	v_lshlrev_b32_e32 v79, 16, v72
	v_fmac_f32_e32 v78, v60, v79
	v_and_b32_e32 v60, 0xffff0000, v68
	v_and_b32_e32 v68, 0xffff0000, v72
	v_fmac_f32_e32 v60, v61, v68
	v_lshlrev_b32_e32 v61, 16, v69
	v_lshlrev_b32_e32 v68, 16, v73
	v_fmac_f32_e32 v61, v62, v68
	v_and_b32_e32 v62, 0xffff0000, v69
	v_and_b32_e32 v68, 0xffff0000, v73
	v_fmac_f32_e32 v62, v63, v68
	v_lshlrev_b32_e32 v63, 16, v70
	v_lshlrev_b32_e32 v68, 16, v74
	v_fmac_f32_e32 v63, v56, v68
	v_and_b32_e32 v68, 0xffff0000, v70
	v_and_b32_e32 v56, 0xffff0000, v74
	v_fmac_f32_e32 v68, v57, v56
	v_lshlrev_b32_e32 v69, 16, v71
	v_lshlrev_b32_e32 v56, 16, v75
	v_fmac_f32_e32 v69, v58, v56
	v_and_b32_e32 v70, 0xffff0000, v71
	v_and_b32_e32 v56, 0xffff0000, v75
	v_fmac_f32_e32 v70, v59, v56
	v_cvt_pk_bf16_f32 v56, v78, v60
	v_cvt_pk_bf16_f32 v57, v61, v62
	v_cvt_pk_bf16_f32 v58, v63, v68
	v_cvt_pk_bf16_f32 v59, v69, v70
	global_store_dwordx4 v[66:67], v[56:59], off
	global_load_dwordx4 v[56:59], v[66:67], off offset:256
	s_nop 0
	global_load_dwordx4 v[60:63], v[76:77], off offset:256
	s_waitcnt vmcnt(1)
	v_lshlrev_b32_e32 v68, 16, v56
	s_waitcnt vmcnt(0)
	v_lshlrev_b32_e32 v69, 16, v60
	v_fmac_f32_e32 v68, v52, v69
	v_and_b32_e32 v52, 0xffff0000, v56
	v_and_b32_e32 v56, 0xffff0000, v60
	v_fmac_f32_e32 v52, v53, v56
	v_lshlrev_b32_e32 v53, 16, v57
	v_lshlrev_b32_e32 v56, 16, v61
	v_fmac_f32_e32 v53, v54, v56
	v_and_b32_e32 v54, 0xffff0000, v57
	v_and_b32_e32 v56, 0xffff0000, v61
	v_fmac_f32_e32 v54, v55, v56
	v_lshlrev_b32_e32 v55, 16, v58
	v_lshlrev_b32_e32 v56, 16, v62
	v_fmac_f32_e32 v55, v48, v56
	v_and_b32_e32 v56, 0xffff0000, v58
	v_and_b32_e32 v48, 0xffff0000, v62
	v_fmac_f32_e32 v56, v49, v48
	v_lshlrev_b32_e32 v57, 16, v59
	v_lshlrev_b32_e32 v48, 16, v63
	v_fmac_f32_e32 v57, v50, v48
	v_and_b32_e32 v58, 0xffff0000, v59
	v_and_b32_e32 v48, 0xffff0000, v63
	v_fmac_f32_e32 v58, v51, v48
	v_cvt_pk_bf16_f32 v48, v68, v52
	v_cvt_pk_bf16_f32 v49, v53, v54
	v_cvt_pk_bf16_f32 v50, v55, v56
	v_cvt_pk_bf16_f32 v51, v57, v58
	global_store_dwordx4 v[66:67], v[48:51], off offset:256
	s_nop 1
	v_add_u32_e32 v48, 0x90, v146
	v_ashrrev_i32_e32 v49, 31, v48
	v_lshlrev_b64 v[48:49], 11, v[48:49]
	v_lshl_add_u64 v[48:49], s[4:5], 0, v[48:49]
	v_lshl_add_u64 v[48:49], v[48:49], 0, v[148:149]
	v_add_co_u32_e32 v58, vcc, s3, v48
	global_load_dwordx4 v[50:53], v[48:49], off
	s_nop 0
	v_addc_co_u32_e32 v59, vcc, 0, v49, vcc
	global_load_dwordx4 v[54:57], v[58:59], off
	s_waitcnt vmcnt(1)
	v_lshlrev_b32_e32 v60, 16, v50
	s_waitcnt vmcnt(0)
	v_lshlrev_b32_e32 v61, 16, v54
	v_fmac_f32_e32 v60, v44, v61
	v_and_b32_e32 v44, 0xffff0000, v50
	v_and_b32_e32 v50, 0xffff0000, v54
	v_fmac_f32_e32 v44, v45, v50
	v_lshlrev_b32_e32 v45, 16, v51
	v_lshlrev_b32_e32 v50, 16, v55
	v_fmac_f32_e32 v45, v46, v50
	v_and_b32_e32 v46, 0xffff0000, v51
	v_and_b32_e32 v50, 0xffff0000, v55
	v_fmac_f32_e32 v46, v47, v50
	v_lshlrev_b32_e32 v47, 16, v52
	v_lshlrev_b32_e32 v50, 16, v56
	v_fmac_f32_e32 v47, v40, v50
	v_and_b32_e32 v50, 0xffff0000, v52
	v_and_b32_e32 v40, 0xffff0000, v56
	v_fmac_f32_e32 v50, v41, v40
	v_lshlrev_b32_e32 v51, 16, v53
	v_lshlrev_b32_e32 v40, 16, v57
	v_fmac_f32_e32 v51, v42, v40
	v_and_b32_e32 v52, 0xffff0000, v53
	v_and_b32_e32 v40, 0xffff0000, v57
	v_fmac_f32_e32 v52, v43, v40
	v_cvt_pk_bf16_f32 v40, v60, v44
	v_cvt_pk_bf16_f32 v41, v45, v46
	v_cvt_pk_bf16_f32 v42, v47, v50
	v_cvt_pk_bf16_f32 v43, v51, v52
	global_store_dwordx4 v[48:49], v[40:43], off
	global_load_dwordx4 v[40:43], v[48:49], off offset:256
	s_nop 0
	global_load_dwordx4 v[44:47], v[58:59], off offset:256
	s_waitcnt vmcnt(1)
	v_lshlrev_b32_e32 v50, 16, v40
	s_waitcnt vmcnt(0)
	v_lshlrev_b32_e32 v51, 16, v44
	v_fmac_f32_e32 v50, v36, v51
	v_and_b32_e32 v36, 0xffff0000, v40
	v_and_b32_e32 v40, 0xffff0000, v44
	v_fmac_f32_e32 v36, v37, v40
	v_lshlrev_b32_e32 v37, 16, v41
	v_lshlrev_b32_e32 v40, 16, v45
	v_fmac_f32_e32 v37, v38, v40
	v_and_b32_e32 v38, 0xffff0000, v41
	v_and_b32_e32 v40, 0xffff0000, v45
	v_fmac_f32_e32 v38, v39, v40
	v_lshlrev_b32_e32 v39, 16, v42
	v_lshlrev_b32_e32 v40, 16, v46
	v_fmac_f32_e32 v39, v32, v40
	v_and_b32_e32 v40, 0xffff0000, v42
	v_and_b32_e32 v32, 0xffff0000, v46
	v_fmac_f32_e32 v40, v33, v32
	v_lshlrev_b32_e32 v41, 16, v43
	v_lshlrev_b32_e32 v32, 16, v47
	v_fmac_f32_e32 v41, v34, v32
	v_and_b32_e32 v42, 0xffff0000, v43
	v_and_b32_e32 v32, 0xffff0000, v47
	v_fmac_f32_e32 v42, v35, v32
	v_cvt_pk_bf16_f32 v32, v50, v36
	v_cvt_pk_bf16_f32 v33, v37, v38
	v_cvt_pk_bf16_f32 v34, v39, v40
	v_cvt_pk_bf16_f32 v35, v41, v42
	global_store_dwordx4 v[48:49], v[32:35], off offset:256
	s_nop 1
	v_add_u32_e32 v32, 0xa0, v146
	v_ashrrev_i32_e32 v33, 31, v32
	v_lshlrev_b64 v[32:33], 11, v[32:33]
	v_lshl_add_u64 v[32:33], s[4:5], 0, v[32:33]
	v_lshl_add_u64 v[32:33], v[32:33], 0, v[148:149]
	v_add_co_u32_e32 v42, vcc, s3, v32
	global_load_dwordx4 v[34:37], v[32:33], off
	s_nop 0
	v_addc_co_u32_e32 v43, vcc, 0, v33, vcc
	global_load_dwordx4 v[38:41], v[42:43], off
	s_waitcnt vmcnt(1)
	v_lshlrev_b32_e32 v44, 16, v34
	s_waitcnt vmcnt(0)
	v_lshlrev_b32_e32 v45, 16, v38
	v_fmac_f32_e32 v44, v28, v45
	v_and_b32_e32 v28, 0xffff0000, v34
	v_and_b32_e32 v34, 0xffff0000, v38
	v_fmac_f32_e32 v28, v29, v34
	v_lshlrev_b32_e32 v29, 16, v35
	v_lshlrev_b32_e32 v34, 16, v39
	v_fmac_f32_e32 v29, v30, v34
	v_and_b32_e32 v30, 0xffff0000, v35
	v_and_b32_e32 v34, 0xffff0000, v39
	v_fmac_f32_e32 v30, v31, v34
	v_lshlrev_b32_e32 v31, 16, v36
	v_lshlrev_b32_e32 v34, 16, v40
	v_fmac_f32_e32 v31, v24, v34
	v_and_b32_e32 v34, 0xffff0000, v36
	v_and_b32_e32 v24, 0xffff0000, v40
	v_fmac_f32_e32 v34, v25, v24
	v_lshlrev_b32_e32 v35, 16, v37
	v_lshlrev_b32_e32 v24, 16, v41
	v_fmac_f32_e32 v35, v26, v24
	v_and_b32_e32 v36, 0xffff0000, v37
	v_and_b32_e32 v24, 0xffff0000, v41
	v_fmac_f32_e32 v36, v27, v24
	v_cvt_pk_bf16_f32 v24, v44, v28
	v_cvt_pk_bf16_f32 v25, v29, v30
	v_cvt_pk_bf16_f32 v26, v31, v34
	v_cvt_pk_bf16_f32 v27, v35, v36
	global_store_dwordx4 v[32:33], v[24:27], off
	global_load_dwordx4 v[24:27], v[32:33], off offset:256
	s_nop 0
	global_load_dwordx4 v[28:31], v[42:43], off offset:256
	s_waitcnt vmcnt(1)
	v_lshlrev_b32_e32 v34, 16, v24
	s_waitcnt vmcnt(0)
	v_lshlrev_b32_e32 v35, 16, v28
	v_fmac_f32_e32 v34, v20, v35
	v_and_b32_e32 v20, 0xffff0000, v24
	v_and_b32_e32 v24, 0xffff0000, v28
	v_fmac_f32_e32 v20, v21, v24
	v_lshlrev_b32_e32 v21, 16, v25
	v_lshlrev_b32_e32 v24, 16, v29
	v_fmac_f32_e32 v21, v22, v24
	v_and_b32_e32 v22, 0xffff0000, v25
	v_and_b32_e32 v24, 0xffff0000, v29
	v_fmac_f32_e32 v22, v23, v24
	v_lshlrev_b32_e32 v23, 16, v26
	v_lshlrev_b32_e32 v24, 16, v30
	v_fmac_f32_e32 v23, v16, v24
	v_and_b32_e32 v24, 0xffff0000, v26
	v_and_b32_e32 v16, 0xffff0000, v30
	v_fmac_f32_e32 v24, v17, v16
	v_lshlrev_b32_e32 v25, 16, v27
	v_lshlrev_b32_e32 v16, 16, v31
	v_fmac_f32_e32 v25, v18, v16
	v_and_b32_e32 v26, 0xffff0000, v27
	v_and_b32_e32 v16, 0xffff0000, v31
	v_fmac_f32_e32 v26, v19, v16
	v_cvt_pk_bf16_f32 v16, v34, v20
	v_cvt_pk_bf16_f32 v17, v21, v22
	v_cvt_pk_bf16_f32 v18, v23, v24
	v_cvt_pk_bf16_f32 v19, v25, v26
	global_store_dwordx4 v[32:33], v[16:19], off offset:256
	s_nop 1
	v_add_u32_e32 v16, 0xb0, v146
	v_ashrrev_i32_e32 v17, 31, v16
	v_lshlrev_b64 v[16:17], 11, v[16:17]
	v_lshl_add_u64 v[16:17], s[4:5], 0, v[16:17]
	v_lshl_add_u64 v[16:17], v[16:17], 0, v[148:149]
	v_add_co_u32_e32 v26, vcc, s3, v16
	global_load_dwordx4 v[18:21], v[16:17], off
	s_nop 0
	v_addc_co_u32_e32 v27, vcc, 0, v17, vcc
	global_load_dwordx4 v[22:25], v[26:27], off
	s_mov_b64 s[4:5], -1
	s_andn2_b64 vcc, exec, s[38:39]
	s_waitcnt vmcnt(1)
	v_lshlrev_b32_e32 v28, 16, v18
	s_waitcnt vmcnt(0)
	v_lshlrev_b32_e32 v29, 16, v22
	v_fmac_f32_e32 v28, v12, v29
	v_and_b32_e32 v12, 0xffff0000, v18
	v_and_b32_e32 v18, 0xffff0000, v22
	v_fmac_f32_e32 v12, v13, v18
	v_lshlrev_b32_e32 v13, 16, v19
	v_lshlrev_b32_e32 v18, 16, v23
	v_fmac_f32_e32 v13, v14, v18
	v_and_b32_e32 v14, 0xffff0000, v19
	v_and_b32_e32 v18, 0xffff0000, v23
	v_fmac_f32_e32 v14, v15, v18
	v_lshlrev_b32_e32 v15, 16, v20
	v_lshlrev_b32_e32 v18, 16, v24
	v_fmac_f32_e32 v15, v8, v18
	v_and_b32_e32 v18, 0xffff0000, v20
	v_and_b32_e32 v8, 0xffff0000, v24
	v_fmac_f32_e32 v18, v9, v8
	v_lshlrev_b32_e32 v19, 16, v21
	v_lshlrev_b32_e32 v8, 16, v25
	v_fmac_f32_e32 v19, v10, v8
	v_and_b32_e32 v20, 0xffff0000, v21
	v_and_b32_e32 v8, 0xffff0000, v25
	v_fmac_f32_e32 v20, v11, v8
	v_cvt_pk_bf16_f32 v8, v28, v12
	v_cvt_pk_bf16_f32 v9, v13, v14
	v_cvt_pk_bf16_f32 v10, v15, v18
	v_cvt_pk_bf16_f32 v11, v19, v20
	global_store_dwordx4 v[16:17], v[8:11], off
	global_load_dwordx4 v[8:11], v[16:17], off offset:256
	s_nop 0
	global_load_dwordx4 v[12:15], v[26:27], off offset:256
	s_waitcnt vmcnt(1)
	v_lshlrev_b32_e32 v18, 16, v8
	s_waitcnt vmcnt(0)
	v_lshlrev_b32_e32 v19, 16, v12
	v_fmac_f32_e32 v18, v4, v19
	v_and_b32_e32 v4, 0xffff0000, v8
	v_and_b32_e32 v8, 0xffff0000, v12
	v_fmac_f32_e32 v4, v5, v8
	v_lshlrev_b32_e32 v5, 16, v9
	v_lshlrev_b32_e32 v8, 16, v13
	v_fmac_f32_e32 v5, v6, v8
	v_and_b32_e32 v6, 0xffff0000, v9
	v_and_b32_e32 v8, 0xffff0000, v13
	v_fmac_f32_e32 v6, v7, v8
	v_lshlrev_b32_e32 v7, 16, v10
	v_lshlrev_b32_e32 v8, 16, v14
	v_fmac_f32_e32 v7, v0, v8
	v_and_b32_e32 v8, 0xffff0000, v10
	v_and_b32_e32 v0, 0xffff0000, v14
	v_fmac_f32_e32 v8, v1, v0
	v_lshlrev_b32_e32 v9, 16, v11
	v_lshlrev_b32_e32 v0, 16, v15
	v_fmac_f32_e32 v9, v2, v0
	v_and_b32_e32 v10, 0xffff0000, v11
	v_and_b32_e32 v0, 0xffff0000, v15
	v_fmac_f32_e32 v10, v3, v0
	v_cvt_pk_bf16_f32 v0, v18, v4
	v_cvt_pk_bf16_f32 v1, v5, v6
	v_cvt_pk_bf16_f32 v2, v7, v8
	v_cvt_pk_bf16_f32 v3, v9, v10
	global_store_dwordx4 v[16:17], v[0:3], off offset:256
.Lao_done:
	s_cbranch_vccnz .LBB0_236
	s_andn2_b64 vcc, exec, s[0:1]
	s_cbranch_vccnz .LBB0_235
	s_barrier
	s_branch .LBB0_235
.LBB0_250:
	s_waitcnt vmcnt(0)
	v_readlane_b32 s18, v254, 59
	v_readlane_b32 s19, v254, 60
	s_brev_b32 s3, 64
	s_barrier
